# P1 projection and indexer epilogue stores written through (sc1): less L2 write-back left for the grid barrier that follows
# baseline (speedup 1.0000x reference)
; __device__ __forceinline__ float sq4(const f32x4 v) { return (v[0] * v[0] + v[1] * v[1]) + (v[2] * v[2] + v[3] * v[3]); }
; __device__ __forceinline__ u32x4 pack8(const f32x4 a, const f32x4 b) { u32x4 w; w.x = cvt_pk_bf16(a[0], a[1]); w.y = cvt_pk_bf16(a[2], a[3]); w.z = cvt_pk_bf16(b[0], b[1]); w.w = cvt_pk_bf16(b[2], b[3]); return w; }
; __device__ __forceinline__ void rope_cs(const float pf, const f32x4 fr, f32x4& c, f32x4& s) {
; #pragma unroll
;     for (int j = 0; j < 4; ++j) { const float r = __builtin_amdgcn_fractf(pf * fr[j]); c[j] = __builtin_amdgcn_cosf(r); s[j] = __builtin_amdgcn_sinf(r); }
; }
;     __device__ __forceinline__ void operator()(const f32x4 (&acc)[2][2][4][2], const Unit& u, int wr, int wc, int fr, int fq) const {
;     ...
;             for (int m = 0; m < 4; ++m) {
;                 const int row = u.pm * BM + ai * HALF + wr * 64 + m * 16 + fr;
;                 const float r = rri[ai][m];
;                 f32x4 l0 = acc[ai][0][m][0] * r, l1 = acc[ai][0][m][1] * r, h0 = acc[ai][1][m][0] * r, h1 = acc[ai][1][m][1] * r;
;                 if (pn == 1 && wc == 1) { if (fq == 0) *(f32x4*)(WI + (size_t)row * 4) = l0 * 0.0625f; continue; }
;                 if (pn == 1 && wc == 3) { bf16_t* p = VA + (size_t)row * 64 + d0; st16_wt(p, pack8(l0, l1)); st16_wt((p + 32), pack8(h0, h1)); continue; }
;                 if (pn == 1 && wc == 2) {
;                     float ss = (sq4(l0) + sq4(l1)) + (sq4(h0) + sq4(h1));
;                     ss += __shfl_xor(ss, 16); ss += __shfl_xor(ss, 32);
;                     const float rn = rsqrtf(ss * (1.f / 64.f) + EPS);
;                     l0 = l0 * rn * gk0; l1 = l1 * rn * gk1; h0 = h0 * rn * gk2; h1 = h1 * rn * gk3;
;                 }
;                 f32x4 c0, c1, s0, s1; rope_cs(pfi[ai][m], fi0, c0, s0); rope_cs(pfi[ai][m], fi1, c1, s1);
;                 const f32x4 nl0 = l0 * c0 - h0 * s0, nh0 = h0 * c0 + l0 * s0, nl1 = l1 * c1 - h1 * s1, nh1 = h1 * c1 + l1 * s1;
;                 if (pn == 1 && wc == 2) { bf16_t* p = KA + (size_t)row * 64 + d0; st16_wt(p, pack8(nl0, nl1)); st16_wt((p + 32), pack8(nh0, nh1)); continue; }
;                 bf16_t* ph = pn == 0 ? QIH + (size_t)row * 256 + wc * 64 + d0 : KIH + (size_t)row * 64 + d0;
;                 st16_wt(ph, pack8(nl0, nl1)); st16_wt((ph + 32), pack8(nh0, nh1));
.LBB0_590:
	s_waitcnt vmcnt(0)
	v_cvt_f32_i32_e32 v213, v213
	s_and_b64 vcc, exec, s[70:71]
	v_mul_f32_e32 v214, v36, v213
	v_fract_f32_e32 v214, v214
	v_cos_f32_e32 v230, v214
	v_sin_f32_e32 v232, v214
	v_mul_f32_e32 v214, v38, v213
	v_fract_f32_e32 v214, v214
	v_cos_f32_e32 v234, v214
	v_sin_f32_e32 v236, v214
	v_mul_f32_e32 v214, v39, v213
	v_fract_f32_e32 v214, v214
	v_cos_f32_e32 v235, v214
	v_sin_f32_e32 v237, v214
	v_mul_f32_e32 v214, v32, v213
	v_mul_f32_e32 v215, v37, v213
	v_fract_f32_e32 v214, v214
	v_fract_f32_e32 v215, v215
	v_cos_f32_e32 v238, v214
	v_sin_f32_e32 v240, v214
	v_mul_f32_e32 v214, v33, v213
	v_sin_f32_e32 v233, v215
	v_fract_f32_e32 v214, v214
	v_cos_f32_e32 v231, v215
	v_cos_f32_e32 v239, v214
	v_sin_f32_e32 v241, v214
	v_mul_f32_e32 v214, v34, v213
	v_mul_f32_e32 v213, v35, v213
	v_fract_f32_e32 v214, v214
	v_fract_f32_e32 v213, v213
	v_sin_f32_e32 v244, v214
	v_sin_f32_e32 v245, v213
	v_cos_f32_e32 v242, v214
	v_cos_f32_e32 v243, v213
	v_pk_mul_f32 v[216:217], v[232:233], v[164:165]
	v_pk_mul_f32 v[232:233], v[232:233], v[156:157]
	v_pk_fma_f32 v[216:217], v[230:231], v[156:157], v[216:217] neg_lo:[0,0,1] neg_hi:[0,0,1]
	v_pk_mul_f32 v[156:157], v[236:237], v[158:159]
	v_pk_mul_f32 v[214:215], v[236:237], v[166:167]
	v_pk_fma_f32 v[156:157], v[234:235], v[166:167], v[156:157]
	v_pk_mul_f32 v[166:167], v[240:241], v[160:161]
	v_pk_fma_f32 v[214:215], v[234:235], v[158:159], v[214:215] neg_lo:[0,0,1] neg_hi:[0,0,1]
	v_pk_fma_f32 v[158:159], v[230:231], v[164:165], v[232:233]
	v_pk_mul_f32 v[164:165], v[244:245], v[162:163]
	v_pk_fma_f32 v[166:167], v[238:239], v[152:153], v[166:167] neg_lo:[0,0,1] neg_hi:[0,0,1]
	v_pk_mul_f32 v[230:231], v[240:241], v[152:153]
	v_pk_mul_f32 v[152:153], v[244:245], v[154:155]
	v_pk_fma_f32 v[164:165], v[242:243], v[154:155], v[164:165] neg_lo:[0,0,1] neg_hi:[0,0,1]
	v_pk_fma_f32 v[152:153], v[242:243], v[162:163], v[152:153]
	v_pk_fma_f32 v[154:155], v[238:239], v[160:161], v[230:231]
	s_cbranch_vccz .LBB0_592
	v_lshlrev_b64 v[160:161], 9, v[210:211]
	v_lshlrev_b64 v[162:163], 7, v[210:211]
	v_lshl_add_u64 v[160:161], s[54:55], 0, v[160:161]
	v_lshl_add_u64 v[162:163], s[26:27], 0, v[162:163]
	v_cndmask_b32_e64 v161, v163, v161, s[6:7]
	v_cndmask_b32_e64 v160, v162, v160, s[6:7]
	v_lshl_add_u64 v[230:231], v[176:177], 1, v[160:161]
	v_cvt_pk_bf16_f32 v160, v216, v217
	v_cvt_pk_bf16_f32 v161, v214, v215
	v_cvt_pk_bf16_f32 v162, v166, v167
	v_cvt_pk_bf16_f32 v163, v164, v165
	global_store_dwordx4 v[230:231], v[160:163], off sc1
	s_mov_b64 s[0:1], 0
	s_nop 0
	v_cvt_pk_bf16_f32 v160, v158, v159
	v_cvt_pk_bf16_f32 v161, v156, v157
	v_cvt_pk_bf16_f32 v162, v154, v155
	v_cvt_pk_bf16_f32 v163, v152, v153
	global_store_dwordx4 v[230:231], v[160:163], off offset:64 sc1
.LBB0_592:
	s_andn2_b64 vcc, exec, s[0:1]
	s_cbranch_vccnz .LBB0_594
	v_lshlrev_b64 v[160:161], 7, v[210:211]
	v_lshl_add_u64 v[230:231], v[178:179], 0, v[160:161]
	v_cvt_pk_bf16_f32 v160, v216, v217
	v_cvt_pk_bf16_f32 v161, v214, v215
	v_cvt_pk_bf16_f32 v162, v166, v167
	v_cvt_pk_bf16_f32 v163, v164, v165
	global_store_dwordx4 v[230:231], v[160:163], off sc1
	v_cvt_pk_bf16_f32 v158, v158, v159
	v_cvt_pk_bf16_f32 v159, v156, v157
	s_nop 1
	v_cvt_pk_bf16_f32 v160, v154, v155
	v_cvt_pk_bf16_f32 v161, v152, v153
	global_store_dwordx4 v[230:231], v[158:161], off offset:64 sc1

; __device__ __forceinline__ u32x4 pack8(const f32x4 a, const f32x4 b) { u32x4 w; w.x = cvt_pk_bf16(a[0], a[1]); w.y = cvt_pk_bf16(a[2], a[3]); w.z = cvt_pk_bf16(b[0], b[1]); w.w = cvt_pk_bf16(b[2], b[3]); return w; }
;     __device__ __forceinline__ void operator()(const f32x4 (&acc)[2][2][4][2], const Unit& u, int wr, int wc, int fr, int fq) const {
;     ...
;                 if (pn == 1 && wc == 3) { bf16_t* p = VA + (size_t)row * 64 + d0; st16_wt(p, pack8(l0, l1)); st16_wt((p + 32), pack8(h0, h1)); continue; }
.LBB0_595:
	s_and_b64 vcc, exec, s[0:1]
	s_cbranch_vccz .LBB0_597
	v_lshlrev_b64 v[152:153], 7, v[210:211]
	v_lshl_add_u64 v[156:157], v[180:181], 0, v[152:153]
	v_cvt_pk_bf16_f32 v152, v148, v149
	v_cvt_pk_bf16_f32 v153, v150, v151
	v_cvt_pk_bf16_f32 v154, v144, v145
	v_cvt_pk_bf16_f32 v155, v146, v147
	global_store_dwordx4 v[156:157], v[152:155], off sc1
	v_cvt_pk_bf16_f32 v140, v140, v141
	v_cvt_pk_bf16_f32 v141, v142, v143
	v_cvt_pk_bf16_f32 v142, v136, v137
	v_cvt_pk_bf16_f32 v143, v138, v139
	global_store_dwordx4 v[156:157], v[140:143], off offset:64 sc1

;     __device__ __forceinline__ void operator()(const f32x4 (&acc)[2][2][4][2], const Unit& u, int wr, int wc, int fr, int fq) const {
;     ...
;                 if (pn == 1 && wc == 1) { if (fq == 0) *(f32x4*)(WI + (size_t)row * 4) = l0 * 0.0625f; continue; }
.LBB0_598:
	s_andn2_b64 vcc, exec, s[0:1]
	s_cbranch_vccnz .LBB0_602
	s_and_saveexec_b64 s[0:1], s[2:3]
	s_cbranch_execz .LBB0_601
	v_pk_mul_f32 v[138:139], v[150:151], s[56:57] op_sel_hi:[1,0]
	v_pk_mul_f32 v[136:137], v[148:149], s[56:57] op_sel_hi:[1,0]
	v_lshl_add_u64 v[140:141], v[210:211], 4, s[30:31]
	global_store_dwordx4 v[140:141], v[136:139], off sc1

; __device__ __forceinline__ u32x4 pack8(const f32x4 a, const f32x4 b) { u32x4 w; w.x = cvt_pk_bf16(a[0], a[1]); w.y = cvt_pk_bf16(a[2], a[3]); w.z = cvt_pk_bf16(b[0], b[1]); w.w = cvt_pk_bf16(b[2], b[3]); return w; }
; __device__ __forceinline__ void rope_cs(const float pf, const f32x4 fr, f32x4& c, f32x4& s) {
; #pragma unroll
;     for (int j = 0; j < 4; ++j) { const float r = __builtin_amdgcn_fractf(pf * fr[j]); c[j] = __builtin_amdgcn_cosf(r); s[j] = __builtin_amdgcn_sinf(r); }
; }
;     __device__ __forceinline__ void operator()(const f32x4 (&acc)[2][2][4][2], const Unit& u, int wr, int wc, int fr, int fq) const {
;     ...
;                 f32x4 c0, c1, s0, s1; rope_cs(pfi[ai][m], fi0, c0, s0); rope_cs(pfi[ai][m], fi1, c1, s1);
;                 const f32x4 nl0 = l0 * c0 - h0 * s0, nh0 = h0 * c0 + l0 * s0, nl1 = l1 * c1 - h1 * s1, nh1 = h1 * c1 + l1 * s1;
;                 if (pn == 1 && wc == 2) { bf16_t* p = KA + (size_t)row * 64 + d0; st16_wt(p, pack8(nl0, nl1)); st16_wt((p + 32), pack8(nh0, nh1)); continue; }
;                 bf16_t* ph = pn == 0 ? QIH + (size_t)row * 256 + wc * 64 + d0 : KIH + (size_t)row * 64 + d0;
;                 st16_wt(ph, pack8(nl0, nl1)); st16_wt((ph + 32), pack8(nh0, nh1));
.LBB0_607:
	v_cvt_f32_i32_e32 v153, v209
	s_andn2_b64 vcc, exec, s[70:71]
	v_mul_f32_e32 v154, v36, v153
	v_fract_f32_e32 v154, v154
	v_cos_f32_e32 v158, v154
	v_sin_f32_e32 v160, v154
	v_mul_f32_e32 v154, v38, v153
	v_fract_f32_e32 v154, v154
	v_cos_f32_e32 v162, v154
	v_sin_f32_e32 v164, v154
	v_mul_f32_e32 v154, v39, v153
	v_fract_f32_e32 v154, v154
	v_cos_f32_e32 v163, v154
	v_sin_f32_e32 v165, v154
	v_mul_f32_e32 v154, v32, v153
	v_mul_f32_e32 v155, v37, v153
	v_fract_f32_e32 v154, v154
	v_fract_f32_e32 v155, v155
	v_cos_f32_e32 v166, v154
	v_sin_f32_e32 v210, v154
	v_mul_f32_e32 v154, v33, v153
	v_sin_f32_e32 v161, v155
	v_fract_f32_e32 v154, v154
	v_cos_f32_e32 v159, v155
	v_cos_f32_e32 v167, v154
	v_sin_f32_e32 v211, v154
	v_mul_f32_e32 v154, v34, v153
	v_mul_f32_e32 v153, v35, v153
	v_fract_f32_e32 v154, v154
	v_fract_f32_e32 v153, v153
	v_sin_f32_e32 v214, v154
	v_sin_f32_e32 v215, v153
	v_cos_f32_e32 v212, v154
	v_cos_f32_e32 v213, v153
	v_pk_mul_f32 v[156:157], v[160:161], v[148:149]
	v_pk_mul_f32 v[160:161], v[160:161], v[140:141]
	v_pk_fma_f32 v[156:157], v[158:159], v[140:141], v[156:157] neg_lo:[0,0,1] neg_hi:[0,0,1]
	v_pk_mul_f32 v[140:141], v[164:165], v[142:143]
	v_pk_mul_f32 v[154:155], v[164:165], v[150:151]
	v_pk_fma_f32 v[140:141], v[162:163], v[150:151], v[140:141]
	v_pk_mul_f32 v[150:151], v[210:211], v[144:145]
	v_pk_fma_f32 v[154:155], v[162:163], v[142:143], v[154:155] neg_lo:[0,0,1] neg_hi:[0,0,1]
	v_pk_fma_f32 v[142:143], v[158:159], v[148:149], v[160:161]
	v_pk_mul_f32 v[148:149], v[214:215], v[146:147]
	v_pk_fma_f32 v[150:151], v[166:167], v[136:137], v[150:151] neg_lo:[0,0,1] neg_hi:[0,0,1]
	v_pk_mul_f32 v[158:159], v[210:211], v[136:137]
	v_pk_mul_f32 v[136:137], v[214:215], v[138:139]
	v_ashrrev_i32_e32 v153, 31, v152
	v_pk_fma_f32 v[148:149], v[212:213], v[138:139], v[148:149] neg_lo:[0,0,1] neg_hi:[0,0,1]
	v_pk_fma_f32 v[136:137], v[212:213], v[146:147], v[136:137]
	v_pk_fma_f32 v[138:139], v[166:167], v[144:145], v[158:159]
	v_lshlrev_b64 v[144:145], 7, v[152:153]
	s_cbranch_vccnz .LBB0_609
	v_lshlrev_b64 v[146:147], 9, v[152:153]
	v_lshl_add_u64 v[146:147], s[54:55], 0, v[146:147]
	v_lshl_add_u64 v[158:159], s[26:27], 0, v[144:145]
	v_cndmask_b32_e64 v147, v159, v147, s[6:7]
	v_cndmask_b32_e64 v146, v158, v146, s[6:7]
	v_lshl_add_u64 v[146:147], v[176:177], 1, v[146:147]
	v_cvt_pk_bf16_f32 v158, v156, v157
	v_cvt_pk_bf16_f32 v159, v154, v155
	v_cvt_pk_bf16_f32 v160, v150, v151
	v_cvt_pk_bf16_f32 v161, v148, v149
	s_mov_b64 s[0:1], 0
	global_store_dwordx4 v[146:147], v[158:161], off sc1
	s_nop 1
	v_cvt_pk_bf16_f32 v158, v142, v143
	v_cvt_pk_bf16_f32 v159, v140, v141
	v_cvt_pk_bf16_f32 v160, v138, v139
	v_cvt_pk_bf16_f32 v161, v136, v137
	global_store_dwordx4 v[146:147], v[158:161], off offset:64 sc1
.LBB0_609:
	s_andn2_b64 vcc, exec, s[0:1]
	s_cbranch_vccnz .LBB0_611
	v_lshl_add_u64 v[158:159], v[178:179], 0, v[144:145]
	v_cvt_pk_bf16_f32 v144, v156, v157
	v_cvt_pk_bf16_f32 v145, v154, v155
	v_cvt_pk_bf16_f32 v146, v150, v151
	v_cvt_pk_bf16_f32 v147, v148, v149
	global_store_dwordx4 v[158:159], v[144:147], off sc1
	v_cvt_pk_bf16_f32 v142, v142, v143
	v_cvt_pk_bf16_f32 v143, v140, v141
	s_nop 1
	v_cvt_pk_bf16_f32 v144, v138, v139
	v_cvt_pk_bf16_f32 v145, v136, v137
	global_store_dwordx4 v[158:159], v[142:145], off offset:64 sc1

; __device__ __forceinline__ u32x4 pack8(const f32x4 a, const f32x4 b) { u32x4 w; w.x = cvt_pk_bf16(a[0], a[1]); w.y = cvt_pk_bf16(a[2], a[3]); w.z = cvt_pk_bf16(b[0], b[1]); w.w = cvt_pk_bf16(b[2], b[3]); return w; }
;     __device__ __forceinline__ void operator()(const f32x4 (&acc)[2][2][4][2], const Unit& u, int wr, int wc, int fr, int fq) const {
;     ...
;                 if (pn == 1 && wc == 3) { bf16_t* p = VA + (size_t)row * 64 + d0; st16_wt(p, pack8(l0, l1)); st16_wt((p + 32), pack8(h0, h1)); continue; }
.LBB0_612:
	s_and_b64 vcc, exec, s[0:1]
	s_cbranch_vccz .LBB0_614
	v_ashrrev_i32_e32 v153, 31, v152
	v_lshlrev_b64 v[136:137], 7, v[152:153]
	v_lshl_add_u64 v[140:141], v[180:181], 0, v[136:137]
	v_cvt_pk_bf16_f32 v136, v132, v133
	v_cvt_pk_bf16_f32 v137, v134, v135
	v_cvt_pk_bf16_f32 v138, v128, v129
	v_cvt_pk_bf16_f32 v139, v130, v131
	global_store_dwordx4 v[140:141], v[136:139], off sc1
	v_cvt_pk_bf16_f32 v124, v124, v125
	v_cvt_pk_bf16_f32 v125, v126, v127
	v_cvt_pk_bf16_f32 v126, v120, v121
	v_cvt_pk_bf16_f32 v127, v122, v123
	global_store_dwordx4 v[140:141], v[124:127], off offset:64 sc1

;     __device__ __forceinline__ void operator()(const f32x4 (&acc)[2][2][4][2], const Unit& u, int wr, int wc, int fr, int fq) const {
;     ...
;                 if (pn == 1 && wc == 1) { if (fq == 0) *(f32x4*)(WI + (size_t)row * 4) = l0 * 0.0625f; continue; }
.LBB0_615:
	s_andn2_b64 vcc, exec, s[0:1]
	s_cbranch_vccnz .LBB0_619
	s_and_saveexec_b64 s[0:1], s[2:3]
	s_cbranch_execz .LBB0_618
	v_ashrrev_i32_e32 v153, 31, v152
	v_pk_mul_f32 v[122:123], v[134:135], s[56:57] op_sel_hi:[1,0]
	v_pk_mul_f32 v[120:121], v[132:133], s[56:57] op_sel_hi:[1,0]
	v_lshl_add_u64 v[124:125], v[152:153], 4, s[30:31]
	global_store_dwordx4 v[124:125], v[120:123], off sc1

; __device__ __forceinline__ u32x4 pack8(const f32x4 a, const f32x4 b) { u32x4 w; w.x = cvt_pk_bf16(a[0], a[1]); w.y = cvt_pk_bf16(a[2], a[3]); w.z = cvt_pk_bf16(b[0], b[1]); w.w = cvt_pk_bf16(b[2], b[3]); return w; }
; __device__ __forceinline__ void rope_cs(const float pf, const f32x4 fr, f32x4& c, f32x4& s) {
; #pragma unroll
;     for (int j = 0; j < 4; ++j) { const float r = __builtin_amdgcn_fractf(pf * fr[j]); c[j] = __builtin_amdgcn_cosf(r); s[j] = __builtin_amdgcn_sinf(r); }
; }
;     __device__ __forceinline__ void operator()(const f32x4 (&acc)[2][2][4][2], const Unit& u, int wr, int wc, int fr, int fq) const {
;     ...
;                 f32x4 c0, c1, s0, s1; rope_cs(pfi[ai][m], fi0, c0, s0); rope_cs(pfi[ai][m], fi1, c1, s1);
;                 const f32x4 nl0 = l0 * c0 - h0 * s0, nh0 = h0 * c0 + l0 * s0, nl1 = l1 * c1 - h1 * s1, nh1 = h1 * c1 + l1 * s1;
;                 if (pn == 1 && wc == 2) { bf16_t* p = KA + (size_t)row * 64 + d0; st16_wt(p, pack8(nl0, nl1)); st16_wt((p + 32), pack8(nh0, nh1)); continue; }
;                 bf16_t* ph = pn == 0 ? QIH + (size_t)row * 256 + wc * 64 + d0 : KIH + (size_t)row * 64 + d0;
;                 st16_wt(ph, pack8(nl0, nl1)); st16_wt((ph + 32), pack8(nh0, nh1));
.LBB0_624:
	v_cvt_f32_i32_e32 v137, v229
	s_andn2_b64 vcc, exec, s[70:71]
	v_mul_f32_e32 v138, v36, v137
	v_fract_f32_e32 v138, v138
	v_cos_f32_e32 v142, v138
	v_sin_f32_e32 v144, v138
	v_mul_f32_e32 v138, v38, v137
	v_fract_f32_e32 v138, v138
	v_cos_f32_e32 v146, v138
	v_sin_f32_e32 v148, v138
	v_mul_f32_e32 v138, v39, v137
	v_fract_f32_e32 v138, v138
	v_cos_f32_e32 v147, v138
	v_sin_f32_e32 v149, v138
	v_mul_f32_e32 v138, v32, v137
	v_mul_f32_e32 v139, v37, v137
	v_fract_f32_e32 v138, v138
	v_fract_f32_e32 v139, v139
	v_cos_f32_e32 v150, v138
	v_sin_f32_e32 v152, v138
	v_mul_f32_e32 v138, v33, v137
	v_sin_f32_e32 v145, v139
	v_fract_f32_e32 v138, v138
	v_cos_f32_e32 v143, v139
	v_cos_f32_e32 v151, v138
	v_sin_f32_e32 v153, v138
	v_mul_f32_e32 v138, v34, v137
	v_mul_f32_e32 v137, v35, v137
	v_fract_f32_e32 v138, v138
	v_fract_f32_e32 v137, v137
	v_sin_f32_e32 v156, v138
	v_sin_f32_e32 v157, v137
	v_cos_f32_e32 v154, v138
	v_cos_f32_e32 v155, v137
	v_pk_mul_f32 v[140:141], v[144:145], v[132:133]
	v_pk_mul_f32 v[144:145], v[144:145], v[124:125]
	v_pk_fma_f32 v[140:141], v[142:143], v[124:125], v[140:141] neg_lo:[0,0,1] neg_hi:[0,0,1]
	v_pk_mul_f32 v[124:125], v[148:149], v[126:127]
	v_pk_mul_f32 v[138:139], v[148:149], v[134:135]
	v_pk_fma_f32 v[124:125], v[146:147], v[134:135], v[124:125]
	v_pk_mul_f32 v[134:135], v[152:153], v[128:129]
	v_pk_fma_f32 v[138:139], v[146:147], v[126:127], v[138:139] neg_lo:[0,0,1] neg_hi:[0,0,1]
	v_pk_fma_f32 v[126:127], v[142:143], v[132:133], v[144:145]
	v_pk_mul_f32 v[132:133], v[156:157], v[130:131]
	v_pk_fma_f32 v[134:135], v[150:151], v[120:121], v[134:135] neg_lo:[0,0,1] neg_hi:[0,0,1]
	v_pk_mul_f32 v[142:143], v[152:153], v[120:121]
	v_pk_mul_f32 v[120:121], v[156:157], v[122:123]
	v_ashrrev_i32_e32 v137, 31, v136
	v_pk_fma_f32 v[132:133], v[154:155], v[122:123], v[132:133] neg_lo:[0,0,1] neg_hi:[0,0,1]
	v_pk_fma_f32 v[120:121], v[154:155], v[130:131], v[120:121]
	v_pk_fma_f32 v[122:123], v[150:151], v[128:129], v[142:143]
	v_lshlrev_b64 v[128:129], 7, v[136:137]
	s_cbranch_vccnz .LBB0_626
	v_lshlrev_b64 v[130:131], 9, v[136:137]
	v_lshl_add_u64 v[130:131], s[54:55], 0, v[130:131]
	v_lshl_add_u64 v[142:143], s[26:27], 0, v[128:129]
	v_cndmask_b32_e64 v131, v143, v131, s[6:7]
	v_cndmask_b32_e64 v130, v142, v130, s[6:7]
	v_lshl_add_u64 v[130:131], v[176:177], 1, v[130:131]
	v_cvt_pk_bf16_f32 v142, v140, v141
	v_cvt_pk_bf16_f32 v143, v138, v139
	v_cvt_pk_bf16_f32 v144, v134, v135
	v_cvt_pk_bf16_f32 v145, v132, v133
	s_mov_b64 s[0:1], 0
	global_store_dwordx4 v[130:131], v[142:145], off sc1
	s_nop 1
	v_cvt_pk_bf16_f32 v142, v126, v127
	v_cvt_pk_bf16_f32 v143, v124, v125
	v_cvt_pk_bf16_f32 v144, v122, v123
	v_cvt_pk_bf16_f32 v145, v120, v121
	global_store_dwordx4 v[130:131], v[142:145], off offset:64 sc1
.LBB0_626:
	s_andn2_b64 vcc, exec, s[0:1]
	s_cbranch_vccnz .LBB0_628
	v_lshl_add_u64 v[142:143], v[178:179], 0, v[128:129]
	v_cvt_pk_bf16_f32 v128, v140, v141
	v_cvt_pk_bf16_f32 v129, v138, v139
	v_cvt_pk_bf16_f32 v130, v134, v135
	v_cvt_pk_bf16_f32 v131, v132, v133
	global_store_dwordx4 v[142:143], v[128:131], off sc1
	v_cvt_pk_bf16_f32 v126, v126, v127
	v_cvt_pk_bf16_f32 v127, v124, v125
	s_nop 1
	v_cvt_pk_bf16_f32 v128, v122, v123
	v_cvt_pk_bf16_f32 v129, v120, v121
	global_store_dwordx4 v[142:143], v[126:129], off offset:64 sc1

; __device__ __forceinline__ u32x4 pack8(const f32x4 a, const f32x4 b) { u32x4 w; w.x = cvt_pk_bf16(a[0], a[1]); w.y = cvt_pk_bf16(a[2], a[3]); w.z = cvt_pk_bf16(b[0], b[1]); w.w = cvt_pk_bf16(b[2], b[3]); return w; }
;     __device__ __forceinline__ void operator()(const f32x4 (&acc)[2][2][4][2], const Unit& u, int wr, int wc, int fr, int fq) const {
;     ...
;                 if (pn == 1 && wc == 3) { bf16_t* p = VA + (size_t)row * 64 + d0; st16_wt(p, pack8(l0, l1)); st16_wt((p + 32), pack8(h0, h1)); continue; }
.LBB0_629:
	s_and_b64 vcc, exec, s[0:1]
	s_cbranch_vccz .LBB0_631
	v_ashrrev_i32_e32 v137, 31, v136
	v_lshlrev_b64 v[120:121], 7, v[136:137]
	v_lshl_add_u64 v[124:125], v[180:181], 0, v[120:121]
	v_cvt_pk_bf16_f32 v120, v116, v117
	v_cvt_pk_bf16_f32 v121, v118, v119
	v_cvt_pk_bf16_f32 v122, v112, v113
	v_cvt_pk_bf16_f32 v123, v114, v115
	global_store_dwordx4 v[124:125], v[120:123], off sc1
	v_cvt_pk_bf16_f32 v108, v108, v109
	v_cvt_pk_bf16_f32 v109, v110, v111
	v_cvt_pk_bf16_f32 v110, v104, v105
	v_cvt_pk_bf16_f32 v111, v106, v107
	global_store_dwordx4 v[124:125], v[108:111], off offset:64 sc1

;     __device__ __forceinline__ void operator()(const f32x4 (&acc)[2][2][4][2], const Unit& u, int wr, int wc, int fr, int fq) const {
;     ...
;                 if (pn == 1 && wc == 1) { if (fq == 0) *(f32x4*)(WI + (size_t)row * 4) = l0 * 0.0625f; continue; }
.LBB0_632:
	s_andn2_b64 vcc, exec, s[0:1]
	s_cbranch_vccnz .LBB0_636
	s_and_saveexec_b64 s[0:1], s[2:3]
	s_cbranch_execz .LBB0_635
	v_ashrrev_i32_e32 v137, 31, v136
	v_pk_mul_f32 v[106:107], v[118:119], s[56:57] op_sel_hi:[1,0]
	v_pk_mul_f32 v[104:105], v[116:117], s[56:57] op_sel_hi:[1,0]
	v_lshl_add_u64 v[108:109], v[136:137], 4, s[30:31]
	global_store_dwordx4 v[108:109], v[104:107], off sc1

; __device__ __forceinline__ u32x4 pack8(const f32x4 a, const f32x4 b) { u32x4 w; w.x = cvt_pk_bf16(a[0], a[1]); w.y = cvt_pk_bf16(a[2], a[3]); w.z = cvt_pk_bf16(b[0], b[1]); w.w = cvt_pk_bf16(b[2], b[3]); return w; }
; __device__ __forceinline__ void rope_cs(const float pf, const f32x4 fr, f32x4& c, f32x4& s) {
; #pragma unroll
;     for (int j = 0; j < 4; ++j) { const float r = __builtin_amdgcn_fractf(pf * fr[j]); c[j] = __builtin_amdgcn_cosf(r); s[j] = __builtin_amdgcn_sinf(r); }
; }
;     __device__ __forceinline__ void operator()(const f32x4 (&acc)[2][2][4][2], const Unit& u, int wr, int wc, int fr, int fq) const {
;     ...
;                 f32x4 c0, c1, s0, s1; rope_cs(pfi[ai][m], fi0, c0, s0); rope_cs(pfi[ai][m], fi1, c1, s1);
;                 const f32x4 nl0 = l0 * c0 - h0 * s0, nh0 = h0 * c0 + l0 * s0, nl1 = l1 * c1 - h1 * s1, nh1 = h1 * c1 + l1 * s1;
;                 if (pn == 1 && wc == 2) { bf16_t* p = KA + (size_t)row * 64 + d0; st16_wt(p, pack8(nl0, nl1)); st16_wt((p + 32), pack8(nh0, nh1)); continue; }
;                 bf16_t* ph = pn == 0 ? QIH + (size_t)row * 256 + wc * 64 + d0 : KIH + (size_t)row * 64 + d0;
;                 st16_wt(ph, pack8(nl0, nl1)); st16_wt((ph + 32), pack8(nh0, nh1));
.LBB0_641:
	v_cvt_f32_i32_e32 v121, v205
	s_andn2_b64 vcc, exec, s[70:71]
	v_mul_f32_e32 v122, v36, v121
	v_fract_f32_e32 v122, v122
	v_cos_f32_e32 v126, v122
	v_sin_f32_e32 v128, v122
	v_mul_f32_e32 v122, v38, v121
	v_fract_f32_e32 v122, v122
	v_cos_f32_e32 v130, v122
	v_sin_f32_e32 v132, v122
	v_mul_f32_e32 v122, v39, v121
	v_fract_f32_e32 v122, v122
	v_cos_f32_e32 v131, v122
	v_sin_f32_e32 v133, v122
	v_mul_f32_e32 v122, v32, v121
	v_mul_f32_e32 v123, v37, v121
	v_fract_f32_e32 v122, v122
	v_fract_f32_e32 v123, v123
	v_cos_f32_e32 v134, v122
	v_sin_f32_e32 v136, v122
	v_mul_f32_e32 v122, v33, v121
	v_sin_f32_e32 v129, v123
	v_fract_f32_e32 v122, v122
	v_cos_f32_e32 v127, v123
	v_cos_f32_e32 v135, v122
	v_sin_f32_e32 v137, v122
	v_mul_f32_e32 v122, v34, v121
	v_mul_f32_e32 v121, v35, v121
	v_fract_f32_e32 v122, v122
	v_fract_f32_e32 v121, v121
	v_sin_f32_e32 v140, v122
	v_sin_f32_e32 v141, v121
	v_cos_f32_e32 v138, v122
	v_cos_f32_e32 v139, v121
	v_pk_mul_f32 v[124:125], v[128:129], v[116:117]
	v_pk_mul_f32 v[128:129], v[128:129], v[108:109]
	v_pk_fma_f32 v[124:125], v[126:127], v[108:109], v[124:125] neg_lo:[0,0,1] neg_hi:[0,0,1]
	v_pk_mul_f32 v[108:109], v[132:133], v[110:111]
	v_pk_mul_f32 v[122:123], v[132:133], v[118:119]
	v_pk_fma_f32 v[108:109], v[130:131], v[118:119], v[108:109]
	v_pk_mul_f32 v[118:119], v[136:137], v[112:113]
	v_pk_fma_f32 v[122:123], v[130:131], v[110:111], v[122:123] neg_lo:[0,0,1] neg_hi:[0,0,1]
	v_pk_fma_f32 v[110:111], v[126:127], v[116:117], v[128:129]
	v_pk_mul_f32 v[116:117], v[140:141], v[114:115]
	v_pk_fma_f32 v[118:119], v[134:135], v[104:105], v[118:119] neg_lo:[0,0,1] neg_hi:[0,0,1]
	v_pk_mul_f32 v[126:127], v[136:137], v[104:105]
	v_pk_mul_f32 v[104:105], v[140:141], v[106:107]
	v_ashrrev_i32_e32 v121, 31, v120
	v_pk_fma_f32 v[116:117], v[138:139], v[106:107], v[116:117] neg_lo:[0,0,1] neg_hi:[0,0,1]
	v_pk_fma_f32 v[104:105], v[138:139], v[114:115], v[104:105]
	v_pk_fma_f32 v[106:107], v[134:135], v[112:113], v[126:127]
	v_lshlrev_b64 v[112:113], 7, v[120:121]
	s_cbranch_vccnz .LBB0_643
	v_lshlrev_b64 v[114:115], 9, v[120:121]
	v_lshl_add_u64 v[114:115], s[54:55], 0, v[114:115]
	v_lshl_add_u64 v[126:127], s[26:27], 0, v[112:113]
	v_cndmask_b32_e64 v115, v127, v115, s[6:7]
	v_cndmask_b32_e64 v114, v126, v114, s[6:7]
	v_lshl_add_u64 v[114:115], v[176:177], 1, v[114:115]
	v_cvt_pk_bf16_f32 v126, v124, v125
	v_cvt_pk_bf16_f32 v127, v122, v123
	v_cvt_pk_bf16_f32 v128, v118, v119
	v_cvt_pk_bf16_f32 v129, v116, v117
	s_mov_b64 s[0:1], 0
	global_store_dwordx4 v[114:115], v[126:129], off sc1
	s_nop 1
	v_cvt_pk_bf16_f32 v126, v110, v111
	v_cvt_pk_bf16_f32 v127, v108, v109
	v_cvt_pk_bf16_f32 v128, v106, v107
	v_cvt_pk_bf16_f32 v129, v104, v105
	global_store_dwordx4 v[114:115], v[126:129], off offset:64 sc1
.LBB0_643:
	s_andn2_b64 vcc, exec, s[0:1]
	s_cbranch_vccnz .LBB0_645
	v_lshl_add_u64 v[126:127], v[178:179], 0, v[112:113]
	v_cvt_pk_bf16_f32 v112, v124, v125
	v_cvt_pk_bf16_f32 v113, v122, v123
	v_cvt_pk_bf16_f32 v114, v118, v119
	v_cvt_pk_bf16_f32 v115, v116, v117
	global_store_dwordx4 v[126:127], v[112:115], off sc1
	v_cvt_pk_bf16_f32 v110, v110, v111
	v_cvt_pk_bf16_f32 v111, v108, v109
	s_nop 1
	v_cvt_pk_bf16_f32 v112, v106, v107
	v_cvt_pk_bf16_f32 v113, v104, v105
	global_store_dwordx4 v[126:127], v[110:113], off offset:64 sc1

; __device__ __forceinline__ u32x4 pack8(const f32x4 a, const f32x4 b) { u32x4 w; w.x = cvt_pk_bf16(a[0], a[1]); w.y = cvt_pk_bf16(a[2], a[3]); w.z = cvt_pk_bf16(b[0], b[1]); w.w = cvt_pk_bf16(b[2], b[3]); return w; }
;     __device__ __forceinline__ void operator()(const f32x4 (&acc)[2][2][4][2], const Unit& u, int wr, int wc, int fr, int fq) const {
;     ...
;                 if (pn == 1 && wc == 3) { bf16_t* p = VA + (size_t)row * 64 + d0; st16_wt(p, pack8(l0, l1)); st16_wt((p + 32), pack8(h0, h1)); continue; }
.LBB0_646:
	s_and_b64 vcc, exec, s[0:1]
	s_cbranch_vccz .LBB0_648
	v_ashrrev_i32_e32 v121, 31, v120
	v_lshlrev_b64 v[104:105], 7, v[120:121]
	v_lshl_add_u64 v[108:109], v[180:181], 0, v[104:105]
	v_cvt_pk_bf16_f32 v104, v100, v101
	v_cvt_pk_bf16_f32 v105, v102, v103
	v_cvt_pk_bf16_f32 v106, v96, v97
	v_cvt_pk_bf16_f32 v107, v98, v99
	global_store_dwordx4 v[108:109], v[104:107], off sc1
	v_cvt_pk_bf16_f32 v92, v92, v93
	v_cvt_pk_bf16_f32 v93, v94, v95
	v_cvt_pk_bf16_f32 v94, v88, v89
	v_cvt_pk_bf16_f32 v95, v90, v91
	global_store_dwordx4 v[108:109], v[92:95], off offset:64 sc1

;     __device__ __forceinline__ void operator()(const f32x4 (&acc)[2][2][4][2], const Unit& u, int wr, int wc, int fr, int fq) const {
;     ...
;                 if (pn == 1 && wc == 1) { if (fq == 0) *(f32x4*)(WI + (size_t)row * 4) = l0 * 0.0625f; continue; }
.LBB0_649:
	s_andn2_b64 vcc, exec, s[0:1]
	s_cbranch_vccnz .LBB0_653
	s_and_saveexec_b64 s[0:1], s[2:3]
	s_cbranch_execz .LBB0_652
	v_ashrrev_i32_e32 v121, 31, v120
	v_pk_mul_f32 v[90:91], v[102:103], s[56:57] op_sel_hi:[1,0]
	v_pk_mul_f32 v[88:89], v[100:101], s[56:57] op_sel_hi:[1,0]
	v_lshl_add_u64 v[92:93], v[120:121], 4, s[30:31]
	global_store_dwordx4 v[92:93], v[88:91], off sc1

; __device__ __forceinline__ u32x4 pack8(const f32x4 a, const f32x4 b) { u32x4 w; w.x = cvt_pk_bf16(a[0], a[1]); w.y = cvt_pk_bf16(a[2], a[3]); w.z = cvt_pk_bf16(b[0], b[1]); w.w = cvt_pk_bf16(b[2], b[3]); return w; }
; __device__ __forceinline__ void rope_cs(const float pf, const f32x4 fr, f32x4& c, f32x4& s) {
; #pragma unroll
;     for (int j = 0; j < 4; ++j) { const float r = __builtin_amdgcn_fractf(pf * fr[j]); c[j] = __builtin_amdgcn_cosf(r); s[j] = __builtin_amdgcn_sinf(r); }
; }
;     __device__ __forceinline__ void operator()(const f32x4 (&acc)[2][2][4][2], const Unit& u, int wr, int wc, int fr, int fq) const {
;     ...
;                 f32x4 c0, c1, s0, s1; rope_cs(pfi[ai][m], fi0, c0, s0); rope_cs(pfi[ai][m], fi1, c1, s1);
;                 const f32x4 nl0 = l0 * c0 - h0 * s0, nh0 = h0 * c0 + l0 * s0, nl1 = l1 * c1 - h1 * s1, nh1 = h1 * c1 + l1 * s1;
;                 if (pn == 1 && wc == 2) { bf16_t* p = KA + (size_t)row * 64 + d0; st16_wt(p, pack8(nl0, nl1)); st16_wt((p + 32), pack8(nh0, nh1)); continue; }
;                 bf16_t* ph = pn == 0 ? QIH + (size_t)row * 256 + wc * 64 + d0 : KIH + (size_t)row * 64 + d0;
;                 st16_wt(ph, pack8(nl0, nl1)); st16_wt((ph + 32), pack8(nh0, nh1));
.LBB0_658:
	v_cvt_f32_i32_e32 v104, v201
	s_andn2_b64 vcc, exec, s[70:71]
	v_mul_f32_e32 v105, v36, v104
	v_fract_f32_e32 v105, v105
	v_cos_f32_e32 v108, v105
	v_sin_f32_e32 v110, v105
	v_mul_f32_e32 v105, v38, v104
	v_fract_f32_e32 v105, v105
	v_cos_f32_e32 v112, v105
	v_sin_f32_e32 v114, v105
	v_mul_f32_e32 v105, v39, v104
	v_fract_f32_e32 v105, v105
	v_cos_f32_e32 v113, v105
	v_sin_f32_e32 v115, v105
	v_mul_f32_e32 v105, v32, v104
	v_mul_f32_e32 v106, v37, v104
	v_fract_f32_e32 v105, v105
	v_fract_f32_e32 v106, v106
	v_cos_f32_e32 v116, v105
	v_sin_f32_e32 v118, v105
	v_mul_f32_e32 v105, v33, v104
	v_sin_f32_e32 v111, v106
	v_fract_f32_e32 v105, v105
	v_cos_f32_e32 v109, v106
	v_cos_f32_e32 v117, v105
	v_sin_f32_e32 v119, v105
	v_mul_f32_e32 v105, v34, v104
	v_mul_f32_e32 v104, v35, v104
	v_fract_f32_e32 v105, v105
	v_fract_f32_e32 v104, v104
	v_sin_f32_e32 v122, v105
	v_sin_f32_e32 v123, v104
	v_cos_f32_e32 v120, v105
	v_cos_f32_e32 v121, v104
	v_pk_mul_f32 v[106:107], v[110:111], v[100:101]
	v_pk_mul_f32 v[110:111], v[110:111], v[92:93]
	v_pk_fma_f32 v[106:107], v[108:109], v[92:93], v[106:107] neg_lo:[0,0,1] neg_hi:[0,0,1]
	v_pk_mul_f32 v[92:93], v[114:115], v[94:95]
	v_pk_mul_f32 v[104:105], v[114:115], v[102:103]
	v_pk_fma_f32 v[92:93], v[112:113], v[102:103], v[92:93]
	v_pk_mul_f32 v[102:103], v[118:119], v[96:97]
	v_pk_fma_f32 v[104:105], v[112:113], v[94:95], v[104:105] neg_lo:[0,0,1] neg_hi:[0,0,1]
	v_pk_fma_f32 v[94:95], v[108:109], v[100:101], v[110:111]
	v_pk_mul_f32 v[100:101], v[122:123], v[98:99]
	v_pk_fma_f32 v[102:103], v[116:117], v[88:89], v[102:103] neg_lo:[0,0,1] neg_hi:[0,0,1]
	v_pk_mul_f32 v[108:109], v[118:119], v[88:89]
	v_pk_mul_f32 v[88:89], v[122:123], v[90:91]
	v_pk_fma_f32 v[100:101], v[120:121], v[90:91], v[100:101] neg_lo:[0,0,1] neg_hi:[0,0,1]
	v_pk_fma_f32 v[88:89], v[120:121], v[98:99], v[88:89]
	v_pk_fma_f32 v[90:91], v[116:117], v[96:97], v[108:109]
	s_cbranch_vccnz .LBB0_660
	v_lshlrev_b64 v[96:97], 9, v[202:203]
	v_lshlrev_b64 v[98:99], 7, v[202:203]
	v_lshl_add_u64 v[96:97], s[54:55], 0, v[96:97]
	v_lshl_add_u64 v[98:99], s[26:27], 0, v[98:99]
	v_cndmask_b32_e64 v97, v99, v97, s[6:7]
	v_cndmask_b32_e64 v96, v98, v96, s[6:7]
	v_lshl_add_u64 v[108:109], v[176:177], 1, v[96:97]
	v_cvt_pk_bf16_f32 v96, v106, v107
	v_cvt_pk_bf16_f32 v97, v104, v105
	v_cvt_pk_bf16_f32 v98, v102, v103
	v_cvt_pk_bf16_f32 v99, v100, v101
	s_mov_b64 s[0:1], 0
	global_store_dwordx4 v[108:109], v[96:99], off sc1
	s_nop 1
	v_cvt_pk_bf16_f32 v96, v94, v95
	v_cvt_pk_bf16_f32 v97, v92, v93
	v_cvt_pk_bf16_f32 v98, v90, v91
	v_cvt_pk_bf16_f32 v99, v88, v89
	global_store_dwordx4 v[108:109], v[96:99], off offset:64 sc1
.LBB0_660:
	s_andn2_b64 vcc, exec, s[0:1]
	s_cbranch_vccnz .LBB0_662
	v_lshlrev_b64 v[96:97], 7, v[202:203]
	v_lshl_add_u64 v[108:109], v[178:179], 0, v[96:97]
	v_cvt_pk_bf16_f32 v96, v106, v107
	v_cvt_pk_bf16_f32 v97, v104, v105
	v_cvt_pk_bf16_f32 v98, v102, v103
	v_cvt_pk_bf16_f32 v99, v100, v101
	global_store_dwordx4 v[108:109], v[96:99], off sc1
	v_cvt_pk_bf16_f32 v94, v94, v95
	v_cvt_pk_bf16_f32 v95, v92, v93
	s_nop 1
	v_cvt_pk_bf16_f32 v96, v90, v91
	v_cvt_pk_bf16_f32 v97, v88, v89
	global_store_dwordx4 v[108:109], v[94:97], off offset:64 sc1

; __device__ __forceinline__ u32x4 pack8(const f32x4 a, const f32x4 b) { u32x4 w; w.x = cvt_pk_bf16(a[0], a[1]); w.y = cvt_pk_bf16(a[2], a[3]); w.z = cvt_pk_bf16(b[0], b[1]); w.w = cvt_pk_bf16(b[2], b[3]); return w; }
;     __device__ __forceinline__ void operator()(const f32x4 (&acc)[2][2][4][2], const Unit& u, int wr, int wc, int fr, int fq) const {
;     ...
;                 if (pn == 1 && wc == 3) { bf16_t* p = VA + (size_t)row * 64 + d0; st16_wt(p, pack8(l0, l1)); st16_wt((p + 32), pack8(h0, h1)); continue; }
.LBB0_663:
	s_and_b64 vcc, exec, s[0:1]
	s_cbranch_vccz .LBB0_665
	v_lshlrev_b64 v[88:89], 7, v[202:203]
	v_lshl_add_u64 v[92:93], v[180:181], 0, v[88:89]
	v_cvt_pk_bf16_f32 v88, v84, v85
	v_cvt_pk_bf16_f32 v89, v86, v87
	v_cvt_pk_bf16_f32 v90, v80, v81
	v_cvt_pk_bf16_f32 v91, v82, v83
	global_store_dwordx4 v[92:93], v[88:91], off sc1
	v_cvt_pk_bf16_f32 v76, v76, v77
	v_cvt_pk_bf16_f32 v77, v78, v79
	v_cvt_pk_bf16_f32 v78, v72, v73
	v_cvt_pk_bf16_f32 v79, v74, v75
	global_store_dwordx4 v[92:93], v[76:79], off offset:64 sc1

;     __device__ __forceinline__ void operator()(const f32x4 (&acc)[2][2][4][2], const Unit& u, int wr, int wc, int fr, int fq) const {
;     ...
;                 if (pn == 1 && wc == 1) { if (fq == 0) *(f32x4*)(WI + (size_t)row * 4) = l0 * 0.0625f; continue; }
.LBB0_666:
	s_andn2_b64 vcc, exec, s[0:1]
	s_cbranch_vccnz .LBB0_670
	s_and_saveexec_b64 s[0:1], s[2:3]
	s_cbranch_execz .LBB0_669
	v_pk_mul_f32 v[74:75], v[86:87], s[56:57] op_sel_hi:[1,0]
	v_pk_mul_f32 v[72:73], v[84:85], s[56:57] op_sel_hi:[1,0]
	v_lshl_add_u64 v[76:77], v[202:203], 4, s[30:31]
	global_store_dwordx4 v[76:77], v[72:75], off sc1

; __device__ __forceinline__ u32x4 pack8(const f32x4 a, const f32x4 b) { u32x4 w; w.x = cvt_pk_bf16(a[0], a[1]); w.y = cvt_pk_bf16(a[2], a[3]); w.z = cvt_pk_bf16(b[0], b[1]); w.w = cvt_pk_bf16(b[2], b[3]); return w; }
;     __device__ __forceinline__ void operator()(const f32x4 (&acc)[2][2][4][2], const Unit& u, int wr, int wc, int fr, int fq) const {
;     ...
;                 f32x4 c0, c1, s0, s1; rope_cs(pfi[ai][m], fi0, c0, s0); rope_cs(pfi[ai][m], fi1, c1, s1);
;                 const f32x4 nl0 = l0 * c0 - h0 * s0, nh0 = h0 * c0 + l0 * s0, nl1 = l1 * c1 - h1 * s1, nh1 = h1 * c1 + l1 * s1;
;                 if (pn == 1 && wc == 2) { bf16_t* p = KA + (size_t)row * 64 + d0; st16_wt(p, pack8(nl0, nl1)); st16_wt((p + 32), pack8(nh0, nh1)); continue; }
;                 bf16_t* ph = pn == 0 ? QIH + (size_t)row * 256 + wc * 64 + d0 : KIH + (size_t)row * 64 + d0;
;                 st16_wt(ph, pack8(nl0, nl1)); st16_wt((ph + 32), pack8(nh0, nh1));
.LBB0_675:
	v_cvt_f32_i32_e32 v88, v197
	s_andn2_b64 vcc, exec, s[70:71]
	v_mul_f32_e32 v89, v36, v88
	v_fract_f32_e32 v89, v89
	v_cos_f32_e32 v92, v89
	v_sin_f32_e32 v94, v89
	v_mul_f32_e32 v89, v38, v88
	v_fract_f32_e32 v89, v89
	v_cos_f32_e32 v96, v89
	v_sin_f32_e32 v98, v89
	v_mul_f32_e32 v89, v39, v88
	v_fract_f32_e32 v89, v89
	v_cos_f32_e32 v97, v89
	v_sin_f32_e32 v99, v89
	v_mul_f32_e32 v89, v32, v88
	v_mul_f32_e32 v90, v37, v88
	v_fract_f32_e32 v89, v89
	v_fract_f32_e32 v90, v90
	v_cos_f32_e32 v100, v89
	v_sin_f32_e32 v102, v89
	v_mul_f32_e32 v89, v33, v88
	v_sin_f32_e32 v95, v90
	v_fract_f32_e32 v89, v89
	v_cos_f32_e32 v93, v90
	v_cos_f32_e32 v101, v89
	v_sin_f32_e32 v103, v89
	v_mul_f32_e32 v89, v34, v88
	v_mul_f32_e32 v88, v35, v88
	v_fract_f32_e32 v89, v89
	v_fract_f32_e32 v88, v88
	v_sin_f32_e32 v106, v89
	v_sin_f32_e32 v107, v88
	v_cos_f32_e32 v104, v89
	v_cos_f32_e32 v105, v88
	v_pk_mul_f32 v[90:91], v[94:95], v[84:85]
	v_pk_mul_f32 v[94:95], v[94:95], v[76:77]
	v_pk_fma_f32 v[90:91], v[92:93], v[76:77], v[90:91] neg_lo:[0,0,1] neg_hi:[0,0,1]
	v_pk_mul_f32 v[76:77], v[98:99], v[78:79]
	v_pk_mul_f32 v[88:89], v[98:99], v[86:87]
	v_pk_fma_f32 v[76:77], v[96:97], v[86:87], v[76:77]
	v_pk_mul_f32 v[86:87], v[102:103], v[80:81]
	v_pk_fma_f32 v[88:89], v[96:97], v[78:79], v[88:89] neg_lo:[0,0,1] neg_hi:[0,0,1]
	v_pk_fma_f32 v[78:79], v[92:93], v[84:85], v[94:95]
	v_pk_mul_f32 v[84:85], v[106:107], v[82:83]
	v_pk_fma_f32 v[86:87], v[100:101], v[72:73], v[86:87] neg_lo:[0,0,1] neg_hi:[0,0,1]
	v_pk_mul_f32 v[92:93], v[102:103], v[72:73]
	v_pk_mul_f32 v[72:73], v[106:107], v[74:75]
	v_pk_fma_f32 v[84:85], v[104:105], v[74:75], v[84:85] neg_lo:[0,0,1] neg_hi:[0,0,1]
	v_pk_fma_f32 v[72:73], v[104:105], v[82:83], v[72:73]
	v_pk_fma_f32 v[74:75], v[100:101], v[80:81], v[92:93]
	s_cbranch_vccnz .LBB0_677
	v_lshlrev_b64 v[80:81], 9, v[198:199]
	v_lshlrev_b64 v[82:83], 7, v[198:199]
	v_lshl_add_u64 v[80:81], s[54:55], 0, v[80:81]
	v_lshl_add_u64 v[82:83], s[26:27], 0, v[82:83]
	v_cndmask_b32_e64 v81, v83, v81, s[6:7]
	v_cndmask_b32_e64 v80, v82, v80, s[6:7]
	v_lshl_add_u64 v[92:93], v[176:177], 1, v[80:81]
	v_cvt_pk_bf16_f32 v80, v90, v91
	v_cvt_pk_bf16_f32 v81, v88, v89
	v_cvt_pk_bf16_f32 v82, v86, v87
	v_cvt_pk_bf16_f32 v83, v84, v85
	s_mov_b64 s[0:1], 0
	global_store_dwordx4 v[92:93], v[80:83], off sc1
	s_nop 1
	v_cvt_pk_bf16_f32 v80, v78, v79
	v_cvt_pk_bf16_f32 v81, v76, v77
	v_cvt_pk_bf16_f32 v82, v74, v75
	v_cvt_pk_bf16_f32 v83, v72, v73
	global_store_dwordx4 v[92:93], v[80:83], off offset:64 sc1
.LBB0_677:
	s_andn2_b64 vcc, exec, s[0:1]
	s_cbranch_vccnz .LBB0_679
	v_lshlrev_b64 v[80:81], 7, v[198:199]
	v_lshl_add_u64 v[92:93], v[178:179], 0, v[80:81]
	v_cvt_pk_bf16_f32 v80, v90, v91
	v_cvt_pk_bf16_f32 v81, v88, v89
	v_cvt_pk_bf16_f32 v82, v86, v87
	v_cvt_pk_bf16_f32 v83, v84, v85
	global_store_dwordx4 v[92:93], v[80:83], off sc1
	v_cvt_pk_bf16_f32 v78, v78, v79
	v_cvt_pk_bf16_f32 v79, v76, v77
	s_nop 1
	v_cvt_pk_bf16_f32 v80, v74, v75
	v_cvt_pk_bf16_f32 v81, v72, v73
	global_store_dwordx4 v[92:93], v[78:81], off offset:64 sc1

; __device__ __forceinline__ u32x4 pack8(const f32x4 a, const f32x4 b) { u32x4 w; w.x = cvt_pk_bf16(a[0], a[1]); w.y = cvt_pk_bf16(a[2], a[3]); w.z = cvt_pk_bf16(b[0], b[1]); w.w = cvt_pk_bf16(b[2], b[3]); return w; }
;     __device__ __forceinline__ void operator()(const f32x4 (&acc)[2][2][4][2], const Unit& u, int wr, int wc, int fr, int fq) const {
;     ...
;                 if (pn == 1 && wc == 3) { bf16_t* p = VA + (size_t)row * 64 + d0; st16_wt(p, pack8(l0, l1)); st16_wt((p + 32), pack8(h0, h1)); continue; }
.LBB0_680:
	s_and_b64 vcc, exec, s[0:1]
	s_cbranch_vccz .LBB0_682
	v_lshlrev_b64 v[72:73], 7, v[198:199]
	v_lshl_add_u64 v[76:77], v[180:181], 0, v[72:73]
	v_cvt_pk_bf16_f32 v72, v68, v69
	v_cvt_pk_bf16_f32 v73, v70, v71
	v_cvt_pk_bf16_f32 v74, v64, v65
	v_cvt_pk_bf16_f32 v75, v66, v67
	global_store_dwordx4 v[76:77], v[72:75], off sc1
	v_cvt_pk_bf16_f32 v60, v60, v61
	v_cvt_pk_bf16_f32 v61, v62, v63
	v_cvt_pk_bf16_f32 v62, v56, v57
	v_cvt_pk_bf16_f32 v63, v58, v59
	global_store_dwordx4 v[76:77], v[60:63], off offset:64 sc1

;     __device__ __forceinline__ void operator()(const f32x4 (&acc)[2][2][4][2], const Unit& u, int wr, int wc, int fr, int fq) const {
;     ...
;                 if (pn == 1 && wc == 1) { if (fq == 0) *(f32x4*)(WI + (size_t)row * 4) = l0 * 0.0625f; continue; }
.LBB0_683:
	s_andn2_b64 vcc, exec, s[0:1]
	s_cbranch_vccnz .LBB0_687
	s_and_saveexec_b64 s[0:1], s[2:3]
	s_cbranch_execz .LBB0_686
	v_pk_mul_f32 v[58:59], v[70:71], s[56:57] op_sel_hi:[1,0]
	v_pk_mul_f32 v[56:57], v[68:69], s[56:57] op_sel_hi:[1,0]
	v_lshl_add_u64 v[60:61], v[198:199], 4, s[30:31]
	global_store_dwordx4 v[60:61], v[56:59], off sc1

; __device__ __forceinline__ u32x4 pack8(const f32x4 a, const f32x4 b) { u32x4 w; w.x = cvt_pk_bf16(a[0], a[1]); w.y = cvt_pk_bf16(a[2], a[3]); w.z = cvt_pk_bf16(b[0], b[1]); w.w = cvt_pk_bf16(b[2], b[3]); return w; }
;     __device__ __forceinline__ void operator()(const f32x4 (&acc)[2][2][4][2], const Unit& u, int wr, int wc, int fr, int fq) const {
;     ...
;                 f32x4 c0, c1, s0, s1; rope_cs(pfi[ai][m], fi0, c0, s0); rope_cs(pfi[ai][m], fi1, c1, s1);
;                 const f32x4 nl0 = l0 * c0 - h0 * s0, nh0 = h0 * c0 + l0 * s0, nl1 = l1 * c1 - h1 * s1, nh1 = h1 * c1 + l1 * s1;
;                 if (pn == 1 && wc == 2) { bf16_t* p = KA + (size_t)row * 64 + d0; st16_wt(p, pack8(nl0, nl1)); st16_wt((p + 32), pack8(nh0, nh1)); continue; }
;                 bf16_t* ph = pn == 0 ? QIH + (size_t)row * 256 + wc * 64 + d0 : KIH + (size_t)row * 64 + d0;
;                 st16_wt(ph, pack8(nl0, nl1)); st16_wt((ph + 32), pack8(nh0, nh1));
.LBB0_692:
	v_cvt_f32_i32_e32 v72, v193
	s_andn2_b64 vcc, exec, s[70:71]
	v_mul_f32_e32 v73, v36, v72
	v_fract_f32_e32 v73, v73
	v_cos_f32_e32 v76, v73
	v_sin_f32_e32 v78, v73
	v_mul_f32_e32 v73, v38, v72
	v_fract_f32_e32 v73, v73
	v_cos_f32_e32 v80, v73
	v_sin_f32_e32 v82, v73
	v_mul_f32_e32 v73, v39, v72
	v_fract_f32_e32 v73, v73
	v_cos_f32_e32 v81, v73
	v_sin_f32_e32 v83, v73
	v_mul_f32_e32 v73, v32, v72
	v_mul_f32_e32 v74, v37, v72
	v_fract_f32_e32 v73, v73
	v_fract_f32_e32 v74, v74
	v_cos_f32_e32 v84, v73
	v_sin_f32_e32 v86, v73
	v_mul_f32_e32 v73, v33, v72
	v_sin_f32_e32 v79, v74
	v_fract_f32_e32 v73, v73
	v_cos_f32_e32 v77, v74
	v_cos_f32_e32 v85, v73
	v_sin_f32_e32 v87, v73
	v_mul_f32_e32 v73, v34, v72
	v_mul_f32_e32 v72, v35, v72
	v_fract_f32_e32 v73, v73
	v_fract_f32_e32 v72, v72
	v_sin_f32_e32 v90, v73
	v_sin_f32_e32 v91, v72
	v_cos_f32_e32 v88, v73
	v_cos_f32_e32 v89, v72
	v_pk_mul_f32 v[74:75], v[78:79], v[68:69]
	v_pk_mul_f32 v[78:79], v[78:79], v[60:61]
	v_pk_fma_f32 v[74:75], v[76:77], v[60:61], v[74:75] neg_lo:[0,0,1] neg_hi:[0,0,1]
	v_pk_mul_f32 v[60:61], v[82:83], v[62:63]
	v_pk_mul_f32 v[72:73], v[82:83], v[70:71]
	v_pk_fma_f32 v[60:61], v[80:81], v[70:71], v[60:61]
	v_pk_mul_f32 v[70:71], v[86:87], v[64:65]
	v_pk_fma_f32 v[72:73], v[80:81], v[62:63], v[72:73] neg_lo:[0,0,1] neg_hi:[0,0,1]
	v_pk_fma_f32 v[62:63], v[76:77], v[68:69], v[78:79]
	v_pk_mul_f32 v[68:69], v[90:91], v[66:67]
	v_pk_fma_f32 v[70:71], v[84:85], v[56:57], v[70:71] neg_lo:[0,0,1] neg_hi:[0,0,1]
	v_pk_mul_f32 v[76:77], v[86:87], v[56:57]
	v_pk_mul_f32 v[56:57], v[90:91], v[58:59]
	v_pk_fma_f32 v[68:69], v[88:89], v[58:59], v[68:69] neg_lo:[0,0,1] neg_hi:[0,0,1]
	v_pk_fma_f32 v[56:57], v[88:89], v[66:67], v[56:57]
	v_pk_fma_f32 v[58:59], v[84:85], v[64:65], v[76:77]
	s_cbranch_vccnz .LBB0_694
	v_lshlrev_b64 v[64:65], 9, v[194:195]
	v_lshlrev_b64 v[66:67], 7, v[194:195]
	v_lshl_add_u64 v[64:65], s[54:55], 0, v[64:65]
	v_lshl_add_u64 v[66:67], s[26:27], 0, v[66:67]
	v_cndmask_b32_e64 v65, v67, v65, s[6:7]
	v_cndmask_b32_e64 v64, v66, v64, s[6:7]
	v_lshl_add_u64 v[76:77], v[176:177], 1, v[64:65]
	v_cvt_pk_bf16_f32 v64, v74, v75
	v_cvt_pk_bf16_f32 v65, v72, v73
	v_cvt_pk_bf16_f32 v66, v70, v71
	v_cvt_pk_bf16_f32 v67, v68, v69
	s_mov_b64 s[0:1], 0
	global_store_dwordx4 v[76:77], v[64:67], off sc1
	s_nop 1
	v_cvt_pk_bf16_f32 v64, v62, v63
	v_cvt_pk_bf16_f32 v65, v60, v61
	v_cvt_pk_bf16_f32 v66, v58, v59
	v_cvt_pk_bf16_f32 v67, v56, v57
	global_store_dwordx4 v[76:77], v[64:67], off offset:64 sc1
.LBB0_694:
	s_andn2_b64 vcc, exec, s[0:1]
	s_cbranch_vccnz .LBB0_696
	v_lshlrev_b64 v[64:65], 7, v[194:195]
	v_lshl_add_u64 v[76:77], v[178:179], 0, v[64:65]
	v_cvt_pk_bf16_f32 v64, v74, v75
	v_cvt_pk_bf16_f32 v65, v72, v73
	v_cvt_pk_bf16_f32 v66, v70, v71
	v_cvt_pk_bf16_f32 v67, v68, v69
	global_store_dwordx4 v[76:77], v[64:67], off sc1
	v_cvt_pk_bf16_f32 v62, v62, v63
	v_cvt_pk_bf16_f32 v63, v60, v61
	s_nop 1
	v_cvt_pk_bf16_f32 v64, v58, v59
	v_cvt_pk_bf16_f32 v65, v56, v57
	global_store_dwordx4 v[76:77], v[62:65], off offset:64 sc1

; __device__ __forceinline__ u32x4 pack8(const f32x4 a, const f32x4 b) { u32x4 w; w.x = cvt_pk_bf16(a[0], a[1]); w.y = cvt_pk_bf16(a[2], a[3]); w.z = cvt_pk_bf16(b[0], b[1]); w.w = cvt_pk_bf16(b[2], b[3]); return w; }
;     __device__ __forceinline__ void operator()(const f32x4 (&acc)[2][2][4][2], const Unit& u, int wr, int wc, int fr, int fq) const {
;     ...
;                 if (pn == 1 && wc == 3) { bf16_t* p = VA + (size_t)row * 64 + d0; st16_wt(p, pack8(l0, l1)); st16_wt((p + 32), pack8(h0, h1)); continue; }
.LBB0_697:
	s_and_b64 vcc, exec, s[0:1]
	s_cbranch_vccz .LBB0_699
	v_lshlrev_b64 v[56:57], 7, v[194:195]
	v_lshl_add_u64 v[60:61], v[180:181], 0, v[56:57]
	v_cvt_pk_bf16_f32 v56, v28, v29
	v_cvt_pk_bf16_f32 v57, v30, v31
	v_cvt_pk_bf16_f32 v58, v24, v25
	v_cvt_pk_bf16_f32 v59, v26, v27
	global_store_dwordx4 v[60:61], v[56:59], off sc1
	v_cvt_pk_bf16_f32 v20, v20, v21
	v_cvt_pk_bf16_f32 v21, v22, v23
	v_cvt_pk_bf16_f32 v22, v16, v17
	v_cvt_pk_bf16_f32 v23, v18, v19
	global_store_dwordx4 v[60:61], v[20:23], off offset:64 sc1

;     __device__ __forceinline__ void operator()(const f32x4 (&acc)[2][2][4][2], const Unit& u, int wr, int wc, int fr, int fq) const {
;     ...
;                 if (pn == 1 && wc == 1) { if (fq == 0) *(f32x4*)(WI + (size_t)row * 4) = l0 * 0.0625f; continue; }
.LBB0_700:
	s_andn2_b64 vcc, exec, s[0:1]
	s_cbranch_vccnz .LBB0_704
	s_and_saveexec_b64 s[0:1], s[2:3]
	s_cbranch_execz .LBB0_703
	v_pk_mul_f32 v[18:19], v[30:31], s[56:57] op_sel_hi:[1,0]
	v_pk_mul_f32 v[16:17], v[28:29], s[56:57] op_sel_hi:[1,0]
	v_lshl_add_u64 v[20:21], v[194:195], 4, s[30:31]
	global_store_dwordx4 v[20:21], v[16:19], off sc1

;     __device__ __forceinline__ void operator()(const f32x4 (&acc)[2][2][4][2], const Unit& u, int wr, int wc, int fr, int fq) const {
;     ...
;                 if (pn == 1 && wc == 1) { if (fq == 0) *(f32x4*)(WI + (size_t)row * 4) = l0 * 0.0625f; continue; }
.LBB0_709:
	s_and_saveexec_b64 s[0:1], s[2:3]
	s_cbranch_execz .LBB0_711
	v_pk_mul_f32 v[2:3], v[14:15], s[56:57] op_sel_hi:[1,0]
	v_pk_mul_f32 v[0:1], v[12:13], s[56:57] op_sel_hi:[1,0]
	v_lshl_add_u64 v[4:5], v[190:191], 4, s[30:31]
	global_store_dwordx4 v[4:5], v[0:3], off sc1

; __device__ __forceinline__ u32x4 pack8(const f32x4 a, const f32x4 b) { u32x4 w; w.x = cvt_pk_bf16(a[0], a[1]); w.y = cvt_pk_bf16(a[2], a[3]); w.z = cvt_pk_bf16(b[0], b[1]); w.w = cvt_pk_bf16(b[2], b[3]); return w; }
;     __device__ __forceinline__ void operator()(const f32x4 (&acc)[2][2][4][2], const Unit& u, int wr, int wc, int fr, int fq) const {
;     ...
;                 f32x4 c0, c1, s0, s1; rope_cs(pfi[ai][m], fi0, c0, s0); rope_cs(pfi[ai][m], fi1, c1, s1);
;                 const f32x4 nl0 = l0 * c0 - h0 * s0, nh0 = h0 * c0 + l0 * s0, nl1 = l1 * c1 - h1 * s1, nh1 = h1 * c1 + l1 * s1;
;                 if (pn == 1 && wc == 2) { bf16_t* p = KA + (size_t)row * 64 + d0; st16_wt(p, pack8(nl0, nl1)); st16_wt((p + 32), pack8(nh0, nh1)); continue; }
;                 bf16_t* ph = pn == 0 ? QIH + (size_t)row * 256 + wc * 64 + d0 : KIH + (size_t)row * 64 + d0;
;                 st16_wt(ph, pack8(nl0, nl1)); st16_wt((ph + 32), pack8(nh0, nh1));
.LBB0_713:
	v_cvt_f32_i32_e32 v49, v228
	s_andn2_b64 vcc, exec, s[70:71]
	v_mul_f32_e32 v32, v32, v49
	v_fract_f32_e32 v32, v32
	v_cos_f32_e32 v44, v32
	v_sin_f32_e32 v46, v32
	v_mul_f32_e32 v32, v33, v49
	v_mul_f32_e32 v36, v36, v49
	v_mul_f32_e32 v37, v37, v49
	v_fract_f32_e32 v32, v32
	v_fract_f32_e32 v40, v36
	v_fract_f32_e32 v41, v37
	v_mul_f32_e32 v38, v38, v49
	v_mul_f32_e32 v39, v39, v49
	v_cos_f32_e32 v45, v32
	v_sin_f32_e32 v47, v32
	v_mul_f32_e32 v32, v34, v49
	v_cos_f32_e32 v36, v40
	v_sin_f32_e32 v40, v40
	v_cos_f32_e32 v37, v41
	v_sin_f32_e32 v41, v41
	v_fract_f32_e32 v42, v38
	v_fract_f32_e32 v43, v39
	v_fract_f32_e32 v32, v32
	v_cos_f32_e32 v38, v42
	v_sin_f32_e32 v42, v42
	v_cos_f32_e32 v39, v43
	v_sin_f32_e32 v43, v43
	v_cos_f32_e32 v48, v32
	v_sin_f32_e32 v50, v32
	v_mul_f32_e32 v32, v35, v49
	v_fract_f32_e32 v32, v32
	v_sin_f32_e32 v51, v32
	v_cos_f32_e32 v49, v32
	v_pk_mul_f32 v[34:35], v[40:41], v[28:29]
	v_pk_mul_f32 v[40:41], v[40:41], v[20:21]
	v_pk_fma_f32 v[34:35], v[36:37], v[20:21], v[34:35] neg_lo:[0,0,1] neg_hi:[0,0,1]
	v_pk_mul_f32 v[20:21], v[42:43], v[22:23]
	v_pk_mul_f32 v[32:33], v[42:43], v[30:31]
	v_pk_fma_f32 v[20:21], v[38:39], v[30:31], v[20:21]
	v_pk_mul_f32 v[30:31], v[46:47], v[24:25]
	v_pk_fma_f32 v[32:33], v[38:39], v[22:23], v[32:33] neg_lo:[0,0,1] neg_hi:[0,0,1]
	v_pk_fma_f32 v[22:23], v[36:37], v[28:29], v[40:41]
	v_pk_mul_f32 v[28:29], v[50:51], v[26:27]
	v_pk_fma_f32 v[30:31], v[44:45], v[16:17], v[30:31] neg_lo:[0,0,1] neg_hi:[0,0,1]
	v_pk_mul_f32 v[36:37], v[46:47], v[16:17]
	v_pk_mul_f32 v[16:17], v[50:51], v[18:19]
	v_pk_fma_f32 v[28:29], v[48:49], v[18:19], v[28:29] neg_lo:[0,0,1] neg_hi:[0,0,1]
	v_pk_fma_f32 v[16:17], v[48:49], v[26:27], v[16:17]
	v_pk_fma_f32 v[18:19], v[44:45], v[24:25], v[36:37]
	s_cbranch_vccnz .LBB0_715
	v_lshlrev_b64 v[24:25], 9, v[190:191]
	v_lshlrev_b64 v[26:27], 7, v[190:191]
	v_lshl_add_u64 v[24:25], s[54:55], 0, v[24:25]
	v_lshl_add_u64 v[26:27], s[26:27], 0, v[26:27]
	v_cndmask_b32_e64 v25, v27, v25, s[6:7]
	v_cndmask_b32_e64 v24, v26, v24, s[6:7]
	v_lshl_add_u64 v[36:37], v[176:177], 1, v[24:25]
	v_cvt_pk_bf16_f32 v24, v34, v35
	v_cvt_pk_bf16_f32 v25, v32, v33
	v_cvt_pk_bf16_f32 v26, v30, v31
	v_cvt_pk_bf16_f32 v27, v28, v29
	s_mov_b64 s[0:1], 0
	global_store_dwordx4 v[36:37], v[24:27], off sc1
	s_nop 1
	v_cvt_pk_bf16_f32 v24, v22, v23
	v_cvt_pk_bf16_f32 v25, v20, v21
	v_cvt_pk_bf16_f32 v26, v18, v19
	v_cvt_pk_bf16_f32 v27, v16, v17
	global_store_dwordx4 v[36:37], v[24:27], off offset:64 sc1
.LBB0_715:
	s_andn2_b64 vcc, exec, s[0:1]
	s_cbranch_vccnz .LBB0_717
	v_lshlrev_b64 v[24:25], 7, v[190:191]
	v_lshl_add_u64 v[36:37], v[178:179], 0, v[24:25]
	v_cvt_pk_bf16_f32 v24, v34, v35
	v_cvt_pk_bf16_f32 v25, v32, v33
	v_cvt_pk_bf16_f32 v26, v30, v31
	v_cvt_pk_bf16_f32 v27, v28, v29
	global_store_dwordx4 v[36:37], v[24:27], off sc1
	v_cvt_pk_bf16_f32 v22, v22, v23
	v_cvt_pk_bf16_f32 v23, v20, v21
	s_nop 1
	v_cvt_pk_bf16_f32 v24, v18, v19
	v_cvt_pk_bf16_f32 v25, v16, v17
	global_store_dwordx4 v[36:37], v[22:25], off offset:64 sc1

; __device__ __forceinline__ u32x4 pack8(const f32x4 a, const f32x4 b) { u32x4 w; w.x = cvt_pk_bf16(a[0], a[1]); w.y = cvt_pk_bf16(a[2], a[3]); w.z = cvt_pk_bf16(b[0], b[1]); w.w = cvt_pk_bf16(b[2], b[3]); return w; }
;     __device__ __forceinline__ void operator()(const f32x4 (&acc)[2][2][4][2], const Unit& u, int wr, int wc, int fr, int fq) const {
;     ...
;                 if (pn == 1 && wc == 3) { bf16_t* p = VA + (size_t)row * 64 + d0; st16_wt(p, pack8(l0, l1)); st16_wt((p + 32), pack8(h0, h1)); continue; }
.LBB0_718:
	s_and_b64 vcc, exec, s[0:1]
	s_cbranch_vccz .LBB0_720
	v_lshlrev_b64 v[16:17], 7, v[190:191]
	v_lshl_add_u64 v[20:21], v[180:181], 0, v[16:17]
	v_cvt_pk_bf16_f32 v16, v12, v13
	v_cvt_pk_bf16_f32 v17, v14, v15
	v_cvt_pk_bf16_f32 v18, v8, v9
	v_cvt_pk_bf16_f32 v19, v10, v11
	global_store_dwordx4 v[20:21], v[16:19], off sc1
	v_cvt_pk_bf16_f32 v4, v4, v5
	v_cvt_pk_bf16_f32 v5, v6, v7
	v_cvt_pk_bf16_f32 v6, v0, v1
	v_cvt_pk_bf16_f32 v7, v2, v3
	global_store_dwordx4 v[20:21], v[4:7], off offset:64 sc1

; __device__ __forceinline__ float sq4(const f32x4 v) { return (v[0] * v[0] + v[1] * v[1]) + (v[2] * v[2] + v[3] * v[3]); }
; __device__ __forceinline__ u32x4 pack8(const f32x4 a, const f32x4 b) { u32x4 w; w.x = cvt_pk_bf16(a[0], a[1]); w.y = cvt_pk_bf16(a[2], a[3]); w.z = cvt_pk_bf16(b[0], b[1]); w.w = cvt_pk_bf16(b[2], b[3]); return w; }
; __device__ __forceinline__ f32x4 cvti4(const f32x4 a) { typedef int i32x4_ __attribute__((ext_vector_type(4))); const i32x4_ i = __builtin_bit_cast(i32x4_, a); return (f32x4){(float)i[0], (float)i[1], (float)i[2], (float)i[3]}; }
;     __device__ __forceinline__ void operator()(const f32x4 (&acc)[2][2][4][2], const Unit& u, int wr, int wc, int fr, int fq) const {
;     ...
;                 const int row = u.pm * BM + ai * HALF + wr * 64 + m * 16 + fr;
;                 const float r = rr[ai][m];
;                 f32x4 l0 = cvti4(acc[ai][0][m][0]) * r * s0a, l1 = cvti4(acc[ai][0][m][1]) * r * s0b, h0 = cvti4(acc[ai][1][m][0]) * r * s1a, h1 = cvti4(acc[ai][1][m][1]) * r * s1b;
;                 if (mode == 2) {
;                     float ss = (sq4(l0) + sq4(l1)) + (sq4(h0) + sq4(h1));
;                     ss += __shfl_xor(ss, 16); ss += __shfl_xor(ss, 32);
;                     const float rn = rsqrtf(ss * (1.f / 64.f) + EPS);
;                     l0 = l0 * rn * g0a; l1 = l1 * rn * g0b; h0 = h0 * rn * g1a; h1 = h1 * rn * g1b;
;                     f32x4 c0, c1, s0, s1; rope_cs(pf[ai][m], fr0, c0, s0); rope_cs(pf[ai][m], fr1, c1, s1);
;                     const f32x4 nl0 = l0 * c0 - h0 * s0, nh0 = h0 * c0 + l0 * s0, nl1 = l1 * c1 - h1 * s1, nh1 = h1 * c1 + l1 * s1;
;                     l0 = nl0 * scale; l1 = nl1 * scale; h0 = nh0 * scale; h1 = nh1 * scale;
;                 }
;                 bf16_t* p = dst + (size_t)row * pitch + coff + d0;
;                 st16_wt(p, pack8(l0, l1));
;                 st16_wt((p + 32), pack8(h0, h1));
.LBB0_793:
	s_ashr_i32 s49, s48, 31
	s_lshl_b64 s[0:1], s[48:49], 1
	s_add_u32 s0, s56, s0
	s_addc_u32 s1, s57, s1
	v_lshl_add_u64 v[94:95], v[136:137], 1, s[0:1]
	v_lshlrev_b64 v[208:209], 10, v[216:217]
	v_lshl_add_u64 v[208:209], v[94:95], 0, v[208:209]
	v_cvt_pk_bf16_f32 v216, v200, v201
	v_cvt_pk_bf16_f32 v217, v198, v199
	v_cvt_pk_bf16_f32 v218, v218, v219
	v_cvt_pk_bf16_f32 v219, v194, v195
	global_store_dwordx4 v[208:209], v[216:219], off sc1
	v_cvt_pk_bf16_f32 v194, v206, v207
	v_cvt_pk_bf16_f32 v195, v196, v197
	v_pk_mul_f32 v[176:177], v[214:215], v[176:177] op_sel_hi:[0,1]
	v_cvt_pk_bf16_f32 v196, v204, v205
	v_cvt_pk_bf16_f32 v197, v202, v203
	global_store_dwordx4 v[208:209], v[194:197], off offset:64 sc1
	v_pk_mul_f32 v[180:181], v[214:215], v[180:181] op_sel_hi:[0,1]
	v_pk_mul_f32 v[178:179], v[214:215], v[178:179] op_sel_hi:[0,1]
	v_pk_mul_f32 v[174:175], v[214:215], v[174:175] op_sel_hi:[0,1]
	v_pk_mul_f32 v[194:195], v[32:33], v[176:177]
	v_pk_mul_f32 v[188:189], v[214:215], v[188:189] op_sel_hi:[0,1]
	v_pk_mul_f32 v[176:177], v[214:215], v[186:187] op_sel_hi:[0,1]
	v_pk_mul_f32 v[184:185], v[214:215], v[184:185] op_sel_hi:[0,1]
	v_pk_mul_f32 v[182:183], v[214:215], v[182:183] op_sel_hi:[0,1]
	v_pk_mul_f32 v[178:179], v[38:39], v[178:179]
	v_pk_mul_f32 v[180:181], v[36:37], v[180:181]
	v_pk_mul_f32 v[174:175], v[34:35], v[174:175]
	v_pk_mul_f32 v[176:177], v[30:31], v[176:177]
	v_pk_mul_f32 v[186:187], v[28:29], v[188:189]
	v_pk_mul_f32 v[182:183], v[26:27], v[182:183]
	s_and_b64 vcc, exec, s[6:7]
	v_pk_mul_f32 v[184:185], v[24:25], v[184:185]
	s_cbranch_vccnz .LBB0_795
	v_mov_b32_e32 v196, v181
	v_mov_b32_e32 v197, v187
	v_mov_b32_e32 v188, v180
	v_mov_b32_e32 v189, v186
	v_pk_mul_f32 v[196:197], v[196:197], v[196:197]
	v_mov_b32_e32 v198, v179
	v_mov_b32_e32 v199, v177
	v_pk_fma_f32 v[188:189], v[188:189], v[188:189], v[196:197]
	v_mov_b32_e32 v196, v178
	v_mov_b32_e32 v197, v176
	v_pk_mul_f32 v[198:199], v[198:199], v[198:199]
	v_mov_b32_e32 v200, v175
	v_pk_fma_f32 v[196:197], v[196:197], v[196:197], v[198:199]
	v_mov_b32_e32 v198, v195
	v_mov_b32_e32 v199, v185
	v_pk_add_f32 v[188:189], v[188:189], v[196:197]
	v_mov_b32_e32 v196, v194
	v_mov_b32_e32 v197, v184
	v_pk_mul_f32 v[198:199], v[198:199], v[198:199]
	v_mov_b32_e32 v201, v183
	v_pk_fma_f32 v[196:197], v[196:197], v[196:197], v[198:199]
	v_mov_b32_e32 v198, v174
	v_mov_b32_e32 v199, v182
	v_pk_mul_f32 v[200:201], v[200:201], v[200:201]
	v_mul_f32_e32 v206, v18, v224
	v_pk_fma_f32 v[198:199], v[198:199], v[198:199], v[200:201]
	v_mul_f32_e32 v202, v16, v224
	v_pk_add_f32 v[196:197], v[196:197], v[198:199]
	v_mul_f32_e32 v198, v22, v224
	v_pk_add_f32 v[188:189], v[188:189], v[196:197]
	v_and_b32_e32 v196, 64, v215
	v_add_f32_e32 v188, v188, v189
	v_xor_b32_e32 v189, 16, v215
	v_add_u32_e32 v196, 64, v196
	v_cmp_lt_i32_e32 vcc, v189, v196
	v_fract_f32_e32 v199, v198
	v_cos_f32_e32 v198, v199
	v_cndmask_b32_e32 v189, v215, v189, vcc
	v_lshlrev_b32_e32 v189, 2, v189
	ds_bpermute_b32 v189, v189, v188
	v_sin_f32_e32 v200, v199
	v_mul_f32_e32 v199, v23, v224
	v_fract_f32_e32 v201, v199
	v_fract_f32_e32 v207, v206
	s_waitcnt lgkmcnt(0)
	v_add_f32_e32 v188, v188, v189
	v_xor_b32_e32 v189, 32, v215
	v_cmp_lt_i32_e32 vcc, v189, v196
	v_cos_f32_e32 v199, v201
	v_sin_f32_e32 v201, v201
	v_cndmask_b32_e32 v189, v215, v189, vcc
	v_lshlrev_b32_e32 v189, 2, v189
	ds_bpermute_b32 v189, v189, v188
	v_fract_f32_e32 v203, v202
	v_cos_f32_e32 v206, v207
	v_sin_f32_e32 v208, v207
	v_mul_f32_e32 v207, v19, v224
	s_waitcnt lgkmcnt(0)
	v_add_f32_e32 v188, v188, v189
	v_fmamk_f32 v188, v188, 0x3c800000, v211
	v_mul_f32_e32 v189, 0x4b800000, v188
	v_cmp_gt_f32_e32 vcc, s84, v188
	v_cos_f32_e32 v202, v203
	v_sin_f32_e32 v204, v203
	v_cndmask_b32_e32 v188, v188, v189, vcc
	v_rsq_f32_e32 v188, v188
	v_mul_f32_e32 v203, v17, v224
	v_fract_f32_e32 v209, v207
	v_fract_f32_e32 v205, v203
	v_mul_f32_e32 v189, 0x45800000, v188
	v_cndmask_b32_e32 v188, v188, v189, vcc
	v_pk_mul_f32 v[180:181], v[180:181], v[188:189] op_sel_hi:[1,0]
	v_pk_mul_f32 v[178:179], v[178:179], v[188:189] op_sel_hi:[1,0]
	v_pk_mul_f32 v[194:195], v[194:195], v[188:189] op_sel_hi:[1,0]
	v_pk_mul_f32 v[174:175], v[174:175], v[188:189] op_sel_hi:[1,0]
	v_pk_mul_f32 v[176:177], v[176:177], v[188:189] op_sel_hi:[1,0]
	v_pk_mul_f32 v[186:187], v[186:187], v[188:189] op_sel_hi:[1,0]
	v_pk_mul_f32 v[182:183], v[182:183], v[188:189] op_sel_hi:[1,0]
	v_pk_mul_f32 v[184:185], v[184:185], v[188:189] op_sel_hi:[1,0]
	v_mul_f32_e32 v188, v20, v224
	v_fract_f32_e32 v189, v188
	v_cos_f32_e32 v188, v189
	v_sin_f32_e32 v196, v189
	v_mul_f32_e32 v189, v21, v224
	v_fract_f32_e32 v197, v189
	v_cos_f32_e32 v189, v197
	v_sin_f32_e32 v197, v197
	v_cos_f32_e32 v207, v209
	v_sin_f32_e32 v209, v209
	v_pk_mul_f32 v[176:177], v[10:11], v[176:177]
	v_cos_f32_e32 v203, v205
	v_sin_f32_e32 v205, v205
	v_pk_mul_f32 v[178:179], v[14:15], v[178:179]
	v_pk_mul_f32 v[186:187], v[8:9], v[186:187]
	v_pk_mul_f32 v[216:217], v[200:201], v[176:177]
	v_pk_mul_f32 v[180:181], v[12:13], v[180:181]
	v_pk_mul_f32 v[182:183], v[2:3], v[182:183]
	v_pk_mul_f32 v[218:219], v[196:197], v[186:187]
	v_pk_fma_f32 v[216:217], v[198:199], v[178:179], v[216:217] neg_lo:[0,0,1] neg_hi:[0,0,1]
	v_pk_mul_f32 v[178:179], v[200:201], v[178:179]
	v_pk_mul_f32 v[174:175], v[6:7], v[174:175]
	v_pk_mul_f32 v[194:195], v[4:5], v[194:195]
	v_pk_mul_f32 v[184:185], v[0:1], v[184:185]
	v_pk_fma_f32 v[218:219], v[188:189], v[180:181], v[218:219] neg_lo:[0,0,1] neg_hi:[0,0,1]
	v_pk_mul_f32 v[180:181], v[196:197], v[180:181]
	v_pk_fma_f32 v[176:177], v[198:199], v[176:177], v[178:179]
	v_pk_mul_f32 v[178:179], v[208:209], v[182:183]
	v_pk_fma_f32 v[186:187], v[188:189], v[186:187], v[180:181]
	v_pk_mul_f32 v[180:181], v[204:205], v[184:185]
	v_pk_fma_f32 v[196:197], v[206:207], v[174:175], v[178:179] neg_lo:[0,0,1] neg_hi:[0,0,1]
	v_pk_mul_f32 v[174:175], v[208:209], v[174:175]
	v_pk_mul_f32 v[178:179], v[204:205], v[194:195]
	v_pk_fma_f32 v[188:189], v[202:203], v[194:195], v[180:181] neg_lo:[0,0,1] neg_hi:[0,0,1]
	v_pk_fma_f32 v[184:185], v[202:203], v[184:185], v[178:179]
	v_pk_fma_f32 v[182:183], v[206:207], v[182:183], v[174:175]
	s_mov_b32 s0, s54
	s_mov_b32 s1, s54
	v_pk_mul_f32 v[178:179], s[0:1], v[216:217]
	v_pk_mul_f32 v[180:181], s[54:55], v[218:219]
	v_pk_mul_f32 v[174:175], s[0:1], v[196:197]
	v_pk_mul_f32 v[194:195], s[54:55], v[188:189]
	v_pk_mul_f32 v[176:177], s[0:1], v[176:177]
	v_pk_mul_f32 v[186:187], s[54:55], v[186:187]
	v_pk_mul_f32 v[182:183], s[0:1], v[182:183]
	v_pk_mul_f32 v[184:185], s[54:55], v[184:185]
; __device__ __forceinline__ float sq4(const f32x4 v) { return (v[0] * v[0] + v[1] * v[1]) + (v[2] * v[2] + v[3] * v[3]); }
; __device__ __forceinline__ u32x4 pack8(const f32x4 a, const f32x4 b) { u32x4 w; w.x = cvt_pk_bf16(a[0], a[1]); w.y = cvt_pk_bf16(a[2], a[3]); w.z = cvt_pk_bf16(b[0], b[1]); w.w = cvt_pk_bf16(b[2], b[3]); return w; }
; __device__ __forceinline__ f32x4 cvti4(const f32x4 a) { typedef int i32x4_ __attribute__((ext_vector_type(4))); const i32x4_ i = __builtin_bit_cast(i32x4_, a); return (f32x4){(float)i[0], (float)i[1], (float)i[2], (float)i[3]}; }
;     __device__ __forceinline__ void operator()(const f32x4 (&acc)[2][2][4][2], const Unit& u, int wr, int wc, int fr, int fq) const {
;     ...
;                 const int row = u.pm * BM + ai * HALF + wr * 64 + m * 16 + fr;
;                 const float r = rr[ai][m];
;                 f32x4 l0 = cvti4(acc[ai][0][m][0]) * r * s0a, l1 = cvti4(acc[ai][0][m][1]) * r * s0b, h0 = cvti4(acc[ai][1][m][0]) * r * s1a, h1 = cvti4(acc[ai][1][m][1]) * r * s1b;
;                 if (mode == 2) {
;                     float ss = (sq4(l0) + sq4(l1)) + (sq4(h0) + sq4(h1));
;                     ss += __shfl_xor(ss, 16); ss += __shfl_xor(ss, 32);
;                     const float rn = rsqrtf(ss * (1.f / 64.f) + EPS);
;                     l0 = l0 * rn * g0a; l1 = l1 * rn * g0b; h0 = h0 * rn * g1a; h1 = h1 * rn * g1b;
;                     f32x4 c0, c1, s0, s1; rope_cs(pf[ai][m], fr0, c0, s0); rope_cs(pf[ai][m], fr1, c1, s1);
;                     const f32x4 nl0 = l0 * c0 - h0 * s0, nh0 = h0 * c0 + l0 * s0, nl1 = l1 * c1 - h1 * s1, nh1 = h1 * c1 + l1 * s1;
;                     l0 = nl0 * scale; l1 = nl1 * scale; h0 = nh0 * scale; h1 = nh1 * scale;
;                 }
;                 bf16_t* p = dst + (size_t)row * pitch + coff + d0;
;                 st16_wt(p, pack8(l0, l1));
;                 st16_wt((p + 32), pack8(h0, h1));
.LBB0_795:
	v_lshlrev_b64 v[188:189], 10, v[212:213]
	v_lshl_add_u64 v[188:189], v[94:95], 0, v[188:189]
	v_cvt_pk_bf16_f32 v196, v180, v181
	v_cvt_pk_bf16_f32 v197, v178, v179
	v_cvt_pk_bf16_f32 v198, v194, v195
	v_cvt_pk_bf16_f32 v199, v174, v175
	global_store_dwordx4 v[188:189], v[196:199], off sc1
	v_cvt_pk_bf16_f32 v174, v186, v187
	v_cvt_pk_bf16_f32 v175, v176, v177
	v_pk_mul_f32 v[156:157], v[210:211], v[156:157] op_sel_hi:[0,1]
	v_cvt_pk_bf16_f32 v176, v184, v185
	v_cvt_pk_bf16_f32 v177, v182, v183
	global_store_dwordx4 v[188:189], v[174:177], off offset:64 sc1
	v_pk_mul_f32 v[160:161], v[210:211], v[160:161] op_sel_hi:[0,1]
	v_pk_mul_f32 v[158:159], v[210:211], v[158:159] op_sel_hi:[0,1]
	v_pk_mul_f32 v[154:155], v[210:211], v[154:155] op_sel_hi:[0,1]
	v_pk_mul_f32 v[174:175], v[32:33], v[156:157]
	v_pk_mul_f32 v[168:169], v[210:211], v[168:169] op_sel_hi:[0,1]
	v_pk_mul_f32 v[156:157], v[210:211], v[166:167] op_sel_hi:[0,1]
	v_pk_mul_f32 v[164:165], v[210:211], v[164:165] op_sel_hi:[0,1]
	v_pk_mul_f32 v[162:163], v[210:211], v[162:163] op_sel_hi:[0,1]
	v_pk_mul_f32 v[158:159], v[38:39], v[158:159]
	v_pk_mul_f32 v[160:161], v[36:37], v[160:161]
	v_pk_mul_f32 v[154:155], v[34:35], v[154:155]
	v_pk_mul_f32 v[156:157], v[30:31], v[156:157]
	v_pk_mul_f32 v[166:167], v[28:29], v[168:169]
	v_pk_mul_f32 v[162:163], v[26:27], v[162:163]
	s_and_b64 vcc, exec, s[6:7]
	v_pk_mul_f32 v[164:165], v[24:25], v[164:165]
	s_cbranch_vccnz .LBB0_797
	v_mov_b32_e32 v176, v161
	v_mov_b32_e32 v177, v167
	v_mov_b32_e32 v168, v160
	v_mov_b32_e32 v169, v166
	v_pk_mul_f32 v[176:177], v[176:177], v[176:177]
	v_mov_b32_e32 v178, v159
	v_mov_b32_e32 v179, v157
	v_pk_fma_f32 v[168:169], v[168:169], v[168:169], v[176:177]
	v_mov_b32_e32 v176, v158
	v_mov_b32_e32 v177, v156
	v_pk_mul_f32 v[178:179], v[178:179], v[178:179]
	v_mov_b32_e32 v180, v155
	v_pk_fma_f32 v[176:177], v[176:177], v[176:177], v[178:179]
	v_mov_b32_e32 v178, v175
	v_mov_b32_e32 v179, v165
	v_pk_add_f32 v[168:169], v[168:169], v[176:177]
	v_mov_b32_e32 v176, v174
	v_mov_b32_e32 v177, v164
	v_pk_mul_f32 v[178:179], v[178:179], v[178:179]
	v_mov_b32_e32 v181, v163
	v_pk_fma_f32 v[176:177], v[176:177], v[176:177], v[178:179]
	v_mov_b32_e32 v178, v154
	v_mov_b32_e32 v179, v162
	v_pk_mul_f32 v[180:181], v[180:181], v[180:181]
	v_mul_f32_e32 v186, v18, v223
	v_pk_fma_f32 v[178:179], v[178:179], v[178:179], v[180:181]
	v_mul_f32_e32 v182, v16, v223
	v_pk_add_f32 v[176:177], v[176:177], v[178:179]
	v_mul_f32_e32 v178, v22, v223
	v_pk_add_f32 v[168:169], v[168:169], v[176:177]
	v_and_b32_e32 v176, 64, v215
	v_add_f32_e32 v168, v168, v169
	v_xor_b32_e32 v169, 16, v215
	v_add_u32_e32 v176, 64, v176
	v_cmp_lt_i32_e32 vcc, v169, v176
	v_fract_f32_e32 v179, v178
	v_cos_f32_e32 v178, v179
	v_cndmask_b32_e32 v169, v215, v169, vcc
	v_lshlrev_b32_e32 v169, 2, v169
	ds_bpermute_b32 v169, v169, v168
	v_sin_f32_e32 v180, v179
	v_mul_f32_e32 v179, v23, v223
	v_fract_f32_e32 v181, v179
	v_fract_f32_e32 v187, v186
	s_waitcnt lgkmcnt(0)
	v_add_f32_e32 v168, v168, v169
	v_xor_b32_e32 v169, 32, v215
	v_cmp_lt_i32_e32 vcc, v169, v176
	v_cos_f32_e32 v179, v181
	v_sin_f32_e32 v181, v181
	v_cndmask_b32_e32 v169, v215, v169, vcc
	v_lshlrev_b32_e32 v169, 2, v169
	ds_bpermute_b32 v169, v169, v168
	v_fract_f32_e32 v183, v182
	v_cos_f32_e32 v186, v187
	v_sin_f32_e32 v188, v187
	v_mul_f32_e32 v187, v19, v223
	s_waitcnt lgkmcnt(0)
	v_add_f32_e32 v168, v168, v169
	v_fmamk_f32 v168, v168, 0x3c800000, v211
	v_mul_f32_e32 v169, 0x4b800000, v168
	v_cmp_gt_f32_e32 vcc, s84, v168
	v_cos_f32_e32 v182, v183
	v_sin_f32_e32 v184, v183
	v_cndmask_b32_e32 v168, v168, v169, vcc
	v_rsq_f32_e32 v168, v168
	v_mul_f32_e32 v183, v17, v223
	v_fract_f32_e32 v189, v187
	v_fract_f32_e32 v185, v183
	v_mul_f32_e32 v169, 0x45800000, v168
	v_cndmask_b32_e32 v168, v168, v169, vcc
	v_pk_mul_f32 v[160:161], v[160:161], v[168:169] op_sel_hi:[1,0]
	v_pk_mul_f32 v[158:159], v[158:159], v[168:169] op_sel_hi:[1,0]
	v_pk_mul_f32 v[174:175], v[174:175], v[168:169] op_sel_hi:[1,0]
	v_pk_mul_f32 v[154:155], v[154:155], v[168:169] op_sel_hi:[1,0]
	v_pk_mul_f32 v[156:157], v[156:157], v[168:169] op_sel_hi:[1,0]
	v_pk_mul_f32 v[166:167], v[166:167], v[168:169] op_sel_hi:[1,0]
	v_pk_mul_f32 v[162:163], v[162:163], v[168:169] op_sel_hi:[1,0]
	v_pk_mul_f32 v[164:165], v[164:165], v[168:169] op_sel_hi:[1,0]
	v_mul_f32_e32 v168, v20, v223
	v_fract_f32_e32 v169, v168
	v_cos_f32_e32 v168, v169
	v_sin_f32_e32 v176, v169
	v_mul_f32_e32 v169, v21, v223
	v_fract_f32_e32 v177, v169
	v_cos_f32_e32 v169, v177
	v_sin_f32_e32 v177, v177
	v_cos_f32_e32 v187, v189
	v_sin_f32_e32 v189, v189
	v_pk_mul_f32 v[156:157], v[10:11], v[156:157]
	v_cos_f32_e32 v183, v185
	v_sin_f32_e32 v185, v185
	v_pk_mul_f32 v[158:159], v[14:15], v[158:159]
	v_pk_mul_f32 v[166:167], v[8:9], v[166:167]
	v_pk_mul_f32 v[194:195], v[180:181], v[156:157]
	v_pk_mul_f32 v[160:161], v[12:13], v[160:161]
	v_pk_mul_f32 v[162:163], v[2:3], v[162:163]
	v_pk_mul_f32 v[196:197], v[176:177], v[166:167]
	v_pk_fma_f32 v[194:195], v[178:179], v[158:159], v[194:195] neg_lo:[0,0,1] neg_hi:[0,0,1]
	v_pk_mul_f32 v[158:159], v[180:181], v[158:159]
	v_pk_mul_f32 v[154:155], v[6:7], v[154:155]
	v_pk_mul_f32 v[174:175], v[4:5], v[174:175]
	v_pk_mul_f32 v[164:165], v[0:1], v[164:165]
	v_pk_fma_f32 v[196:197], v[168:169], v[160:161], v[196:197] neg_lo:[0,0,1] neg_hi:[0,0,1]
	v_pk_mul_f32 v[160:161], v[176:177], v[160:161]
	v_pk_fma_f32 v[156:157], v[178:179], v[156:157], v[158:159]
	v_pk_mul_f32 v[158:159], v[188:189], v[162:163]
	v_pk_fma_f32 v[166:167], v[168:169], v[166:167], v[160:161]
	v_pk_mul_f32 v[160:161], v[184:185], v[164:165]
	v_pk_fma_f32 v[176:177], v[186:187], v[154:155], v[158:159] neg_lo:[0,0,1] neg_hi:[0,0,1]
	v_pk_mul_f32 v[154:155], v[188:189], v[154:155]
	v_pk_mul_f32 v[158:159], v[184:185], v[174:175]
	v_pk_fma_f32 v[168:169], v[182:183], v[174:175], v[160:161] neg_lo:[0,0,1] neg_hi:[0,0,1]
	v_pk_fma_f32 v[164:165], v[182:183], v[164:165], v[158:159]
	v_pk_fma_f32 v[162:163], v[186:187], v[162:163], v[154:155]
	s_mov_b32 s0, s54
	s_mov_b32 s1, s54
	v_pk_mul_f32 v[158:159], s[0:1], v[194:195]
	v_pk_mul_f32 v[160:161], s[54:55], v[196:197]
	v_pk_mul_f32 v[154:155], s[0:1], v[176:177]
	v_pk_mul_f32 v[174:175], s[54:55], v[168:169]
	v_pk_mul_f32 v[156:157], s[0:1], v[156:157]
	v_pk_mul_f32 v[166:167], s[54:55], v[166:167]
	v_pk_mul_f32 v[162:163], s[0:1], v[162:163]
	v_pk_mul_f32 v[164:165], s[54:55], v[164:165]
; __device__ __forceinline__ float sq4(const f32x4 v) { return (v[0] * v[0] + v[1] * v[1]) + (v[2] * v[2] + v[3] * v[3]); }
; __device__ __forceinline__ u32x4 pack8(const f32x4 a, const f32x4 b) { u32x4 w; w.x = cvt_pk_bf16(a[0], a[1]); w.y = cvt_pk_bf16(a[2], a[3]); w.z = cvt_pk_bf16(b[0], b[1]); w.w = cvt_pk_bf16(b[2], b[3]); return w; }
; __device__ __forceinline__ f32x4 cvti4(const f32x4 a) { typedef int i32x4_ __attribute__((ext_vector_type(4))); const i32x4_ i = __builtin_bit_cast(i32x4_, a); return (f32x4){(float)i[0], (float)i[1], (float)i[2], (float)i[3]}; }
;     __device__ __forceinline__ void operator()(const f32x4 (&acc)[2][2][4][2], const Unit& u, int wr, int wc, int fr, int fq) const {
;     ...
;                 const int row = u.pm * BM + ai * HALF + wr * 64 + m * 16 + fr;
;                 const float r = rr[ai][m];
;                 f32x4 l0 = cvti4(acc[ai][0][m][0]) * r * s0a, l1 = cvti4(acc[ai][0][m][1]) * r * s0b, h0 = cvti4(acc[ai][1][m][0]) * r * s1a, h1 = cvti4(acc[ai][1][m][1]) * r * s1b;
;                 if (mode == 2) {
;                     float ss = (sq4(l0) + sq4(l1)) + (sq4(h0) + sq4(h1));
;                     ss += __shfl_xor(ss, 16); ss += __shfl_xor(ss, 32);
;                     const float rn = rsqrtf(ss * (1.f / 64.f) + EPS);
;                     l0 = l0 * rn * g0a; l1 = l1 * rn * g0b; h0 = h0 * rn * g1a; h1 = h1 * rn * g1b;
;                     f32x4 c0, c1, s0, s1; rope_cs(pf[ai][m], fr0, c0, s0); rope_cs(pf[ai][m], fr1, c1, s1);
;                     const f32x4 nl0 = l0 * c0 - h0 * s0, nh0 = h0 * c0 + l0 * s0, nl1 = l1 * c1 - h1 * s1, nh1 = h1 * c1 + l1 * s1;
;                     l0 = nl0 * scale; l1 = nl1 * scale; h0 = nh0 * scale; h1 = nh1 * scale;
;                 }
;                 bf16_t* p = dst + (size_t)row * pitch + coff + d0;
;                 st16_wt(p, pack8(l0, l1));
;                 st16_wt((p + 32), pack8(h0, h1));
.LBB0_797:
	v_lshlrev_b64 v[168:169], 10, v[192:193]
	v_lshl_add_u64 v[168:169], v[94:95], 0, v[168:169]
	v_cvt_pk_bf16_f32 v176, v160, v161
	v_cvt_pk_bf16_f32 v177, v158, v159
	v_cvt_pk_bf16_f32 v178, v174, v175
	v_cvt_pk_bf16_f32 v179, v154, v155
	global_store_dwordx4 v[168:169], v[176:179], off sc1
	v_cvt_pk_bf16_f32 v154, v166, v167
	v_cvt_pk_bf16_f32 v155, v156, v157
	v_pk_mul_f32 v[118:119], v[190:191], v[118:119] op_sel_hi:[0,1]
	v_cvt_pk_bf16_f32 v156, v164, v165
	v_cvt_pk_bf16_f32 v157, v162, v163
	global_store_dwordx4 v[168:169], v[154:157], off offset:64 sc1
	v_pk_mul_f32 v[122:123], v[190:191], v[122:123] op_sel_hi:[0,1]
	v_pk_mul_f32 v[120:121], v[190:191], v[120:121] op_sel_hi:[0,1]
	v_pk_mul_f32 v[116:117], v[190:191], v[116:117] op_sel_hi:[0,1]
	v_pk_mul_f32 v[154:155], v[32:33], v[118:119]
	v_pk_mul_f32 v[148:149], v[190:191], v[148:149] op_sel_hi:[0,1]
	v_pk_mul_f32 v[118:119], v[190:191], v[146:147] op_sel_hi:[0,1]
	v_pk_mul_f32 v[126:127], v[190:191], v[126:127] op_sel_hi:[0,1]
	v_pk_mul_f32 v[124:125], v[190:191], v[124:125] op_sel_hi:[0,1]
	v_pk_mul_f32 v[120:121], v[38:39], v[120:121]
	v_pk_mul_f32 v[122:123], v[36:37], v[122:123]
	v_pk_mul_f32 v[116:117], v[34:35], v[116:117]
	v_pk_mul_f32 v[118:119], v[30:31], v[118:119]
	v_pk_mul_f32 v[146:147], v[28:29], v[148:149]
	v_pk_mul_f32 v[124:125], v[26:27], v[124:125]
	s_and_b64 vcc, exec, s[6:7]
	v_pk_mul_f32 v[126:127], v[24:25], v[126:127]
	s_cbranch_vccnz .LBB0_799
	v_mov_b32_e32 v156, v123
	v_mov_b32_e32 v157, v147
	v_mov_b32_e32 v148, v122
	v_mov_b32_e32 v149, v146
	v_pk_mul_f32 v[156:157], v[156:157], v[156:157]
	v_mov_b32_e32 v158, v121
	v_mov_b32_e32 v159, v119
	v_pk_fma_f32 v[148:149], v[148:149], v[148:149], v[156:157]
	v_mov_b32_e32 v156, v120
	v_mov_b32_e32 v157, v118
	v_pk_mul_f32 v[158:159], v[158:159], v[158:159]
	v_mov_b32_e32 v160, v117
	v_pk_fma_f32 v[156:157], v[156:157], v[156:157], v[158:159]
	v_mov_b32_e32 v158, v155
	v_mov_b32_e32 v159, v127
	v_pk_add_f32 v[148:149], v[148:149], v[156:157]
	v_mov_b32_e32 v156, v154
	v_mov_b32_e32 v157, v126
	v_pk_mul_f32 v[158:159], v[158:159], v[158:159]
	v_mov_b32_e32 v161, v125
	v_pk_fma_f32 v[156:157], v[156:157], v[156:157], v[158:159]
	v_mov_b32_e32 v158, v116
	v_mov_b32_e32 v159, v124
	v_pk_mul_f32 v[160:161], v[160:161], v[160:161]
	v_mul_f32_e32 v166, v18, v222
	v_pk_fma_f32 v[158:159], v[158:159], v[158:159], v[160:161]
	v_mul_f32_e32 v162, v16, v222
	v_pk_add_f32 v[156:157], v[156:157], v[158:159]
	v_mul_f32_e32 v158, v22, v222
	v_pk_add_f32 v[148:149], v[148:149], v[156:157]
	v_and_b32_e32 v156, 64, v215
	v_add_f32_e32 v148, v148, v149
	v_xor_b32_e32 v149, 16, v215
	v_add_u32_e32 v156, 64, v156
	v_cmp_lt_i32_e32 vcc, v149, v156
	v_fract_f32_e32 v159, v158
	v_cos_f32_e32 v158, v159
	v_cndmask_b32_e32 v149, v215, v149, vcc
	v_lshlrev_b32_e32 v149, 2, v149
	ds_bpermute_b32 v149, v149, v148
	v_sin_f32_e32 v160, v159
	v_mul_f32_e32 v159, v23, v222
	v_fract_f32_e32 v161, v159
	v_fract_f32_e32 v167, v166
	s_waitcnt lgkmcnt(0)
	v_add_f32_e32 v148, v148, v149
	v_xor_b32_e32 v149, 32, v215
	v_cmp_lt_i32_e32 vcc, v149, v156
	v_cos_f32_e32 v159, v161
	v_sin_f32_e32 v161, v161
	v_cndmask_b32_e32 v149, v215, v149, vcc
	v_lshlrev_b32_e32 v149, 2, v149
	ds_bpermute_b32 v149, v149, v148
	v_fract_f32_e32 v163, v162
	v_cos_f32_e32 v166, v167
	v_sin_f32_e32 v168, v167
	v_mul_f32_e32 v167, v19, v222
	s_waitcnt lgkmcnt(0)
	v_add_f32_e32 v148, v148, v149
	v_fmamk_f32 v148, v148, 0x3c800000, v211
	v_mul_f32_e32 v149, 0x4b800000, v148
	v_cmp_gt_f32_e32 vcc, s84, v148
	v_cos_f32_e32 v162, v163
	v_sin_f32_e32 v164, v163
	v_cndmask_b32_e32 v148, v148, v149, vcc
	v_rsq_f32_e32 v148, v148
	v_mul_f32_e32 v163, v17, v222
	v_fract_f32_e32 v169, v167
	v_fract_f32_e32 v165, v163
	v_mul_f32_e32 v149, 0x45800000, v148
	v_cndmask_b32_e32 v148, v148, v149, vcc
	v_pk_mul_f32 v[122:123], v[122:123], v[148:149] op_sel_hi:[1,0]
	v_pk_mul_f32 v[120:121], v[120:121], v[148:149] op_sel_hi:[1,0]
	v_pk_mul_f32 v[154:155], v[154:155], v[148:149] op_sel_hi:[1,0]
	v_pk_mul_f32 v[116:117], v[116:117], v[148:149] op_sel_hi:[1,0]
	v_pk_mul_f32 v[118:119], v[118:119], v[148:149] op_sel_hi:[1,0]
	v_pk_mul_f32 v[146:147], v[146:147], v[148:149] op_sel_hi:[1,0]
	v_pk_mul_f32 v[124:125], v[124:125], v[148:149] op_sel_hi:[1,0]
	v_pk_mul_f32 v[126:127], v[126:127], v[148:149] op_sel_hi:[1,0]
	v_mul_f32_e32 v148, v20, v222
	v_fract_f32_e32 v149, v148
	v_cos_f32_e32 v148, v149
	v_sin_f32_e32 v156, v149
	v_mul_f32_e32 v149, v21, v222
	v_fract_f32_e32 v157, v149
	v_cos_f32_e32 v149, v157
	v_sin_f32_e32 v157, v157
	v_cos_f32_e32 v167, v169
	v_sin_f32_e32 v169, v169
	v_pk_mul_f32 v[118:119], v[10:11], v[118:119]
	v_cos_f32_e32 v163, v165
	v_sin_f32_e32 v165, v165
	v_pk_mul_f32 v[120:121], v[14:15], v[120:121]
	v_pk_mul_f32 v[146:147], v[8:9], v[146:147]
	v_pk_mul_f32 v[174:175], v[160:161], v[118:119]
	v_pk_mul_f32 v[122:123], v[12:13], v[122:123]
	v_pk_mul_f32 v[124:125], v[2:3], v[124:125]
	v_pk_mul_f32 v[176:177], v[156:157], v[146:147]
	v_pk_fma_f32 v[174:175], v[158:159], v[120:121], v[174:175] neg_lo:[0,0,1] neg_hi:[0,0,1]
	v_pk_mul_f32 v[120:121], v[160:161], v[120:121]
	v_pk_mul_f32 v[116:117], v[6:7], v[116:117]
	v_pk_mul_f32 v[154:155], v[4:5], v[154:155]
	v_pk_mul_f32 v[126:127], v[0:1], v[126:127]
	v_pk_fma_f32 v[176:177], v[148:149], v[122:123], v[176:177] neg_lo:[0,0,1] neg_hi:[0,0,1]
	v_pk_mul_f32 v[122:123], v[156:157], v[122:123]
	v_pk_fma_f32 v[118:119], v[158:159], v[118:119], v[120:121]
	v_pk_mul_f32 v[120:121], v[168:169], v[124:125]
	v_pk_fma_f32 v[146:147], v[148:149], v[146:147], v[122:123]
	v_pk_mul_f32 v[122:123], v[164:165], v[126:127]
	v_pk_fma_f32 v[156:157], v[166:167], v[116:117], v[120:121] neg_lo:[0,0,1] neg_hi:[0,0,1]
	v_pk_mul_f32 v[116:117], v[168:169], v[116:117]
	v_pk_mul_f32 v[120:121], v[164:165], v[154:155]
	v_pk_fma_f32 v[148:149], v[162:163], v[154:155], v[122:123] neg_lo:[0,0,1] neg_hi:[0,0,1]
	v_pk_fma_f32 v[126:127], v[162:163], v[126:127], v[120:121]
	v_pk_fma_f32 v[124:125], v[166:167], v[124:125], v[116:117]
	s_mov_b32 s0, s54
	s_mov_b32 s1, s54
	v_pk_mul_f32 v[120:121], s[0:1], v[174:175]
	v_pk_mul_f32 v[122:123], s[54:55], v[176:177]
	v_pk_mul_f32 v[116:117], s[0:1], v[156:157]
	v_pk_mul_f32 v[154:155], s[54:55], v[148:149]
	v_pk_mul_f32 v[118:119], s[0:1], v[118:119]
	v_pk_mul_f32 v[146:147], s[54:55], v[146:147]
	v_pk_mul_f32 v[124:125], s[0:1], v[124:125]
	v_pk_mul_f32 v[126:127], s[54:55], v[126:127]
; __device__ __forceinline__ float sq4(const f32x4 v) { return (v[0] * v[0] + v[1] * v[1]) + (v[2] * v[2] + v[3] * v[3]); }
; __device__ __forceinline__ u32x4 pack8(const f32x4 a, const f32x4 b) { u32x4 w; w.x = cvt_pk_bf16(a[0], a[1]); w.y = cvt_pk_bf16(a[2], a[3]); w.z = cvt_pk_bf16(b[0], b[1]); w.w = cvt_pk_bf16(b[2], b[3]); return w; }
; __device__ __forceinline__ f32x4 cvti4(const f32x4 a) { typedef int i32x4_ __attribute__((ext_vector_type(4))); const i32x4_ i = __builtin_bit_cast(i32x4_, a); return (f32x4){(float)i[0], (float)i[1], (float)i[2], (float)i[3]}; }
;     __device__ __forceinline__ void operator()(const f32x4 (&acc)[2][2][4][2], const Unit& u, int wr, int wc, int fr, int fq) const {
;     ...
;                 const int row = u.pm * BM + ai * HALF + wr * 64 + m * 16 + fr;
;                 const float r = rr[ai][m];
;                 f32x4 l0 = cvti4(acc[ai][0][m][0]) * r * s0a, l1 = cvti4(acc[ai][0][m][1]) * r * s0b, h0 = cvti4(acc[ai][1][m][0]) * r * s1a, h1 = cvti4(acc[ai][1][m][1]) * r * s1b;
;                 if (mode == 2) {
;                     float ss = (sq4(l0) + sq4(l1)) + (sq4(h0) + sq4(h1));
;                     ss += __shfl_xor(ss, 16); ss += __shfl_xor(ss, 32);
;                     const float rn = rsqrtf(ss * (1.f / 64.f) + EPS);
;                     l0 = l0 * rn * g0a; l1 = l1 * rn * g0b; h0 = h0 * rn * g1a; h1 = h1 * rn * g1b;
;                     f32x4 c0, c1, s0, s1; rope_cs(pf[ai][m], fr0, c0, s0); rope_cs(pf[ai][m], fr1, c1, s1);
;                     const f32x4 nl0 = l0 * c0 - h0 * s0, nh0 = h0 * c0 + l0 * s0, nl1 = l1 * c1 - h1 * s1, nh1 = h1 * c1 + l1 * s1;
;                     l0 = nl0 * scale; l1 = nl1 * scale; h0 = nh0 * scale; h1 = nh1 * scale;
;                 }
;                 bf16_t* p = dst + (size_t)row * pitch + coff + d0;
;                 st16_wt(p, pack8(l0, l1));
;                 st16_wt((p + 32), pack8(h0, h1));
.LBB0_799:
	v_lshlrev_b64 v[148:149], 10, v[172:173]
	v_lshl_add_u64 v[148:149], v[94:95], 0, v[148:149]
	v_cvt_pk_bf16_f32 v156, v122, v123
	v_cvt_pk_bf16_f32 v157, v120, v121
	v_cvt_pk_bf16_f32 v158, v154, v155
	v_cvt_pk_bf16_f32 v159, v116, v117
	global_store_dwordx4 v[148:149], v[156:159], off sc1
	v_cvt_pk_bf16_f32 v116, v146, v147
	v_cvt_pk_bf16_f32 v117, v118, v119
	v_pk_mul_f32 v[98:99], v[170:171], v[98:99] op_sel_hi:[0,1]
	v_cvt_pk_bf16_f32 v118, v126, v127
	v_cvt_pk_bf16_f32 v119, v124, v125
	global_store_dwordx4 v[148:149], v[116:119], off offset:64 sc1
	v_pk_mul_f32 v[102:103], v[170:171], v[102:103] op_sel_hi:[0,1]
	v_pk_mul_f32 v[100:101], v[170:171], v[100:101] op_sel_hi:[0,1]
	v_pk_mul_f32 v[96:97], v[170:171], v[96:97] op_sel_hi:[0,1]
	v_pk_mul_f32 v[116:117], v[32:33], v[98:99]
	v_pk_mul_f32 v[110:111], v[170:171], v[110:111] op_sel_hi:[0,1]
	v_pk_mul_f32 v[98:99], v[170:171], v[108:109] op_sel_hi:[0,1]
	v_pk_mul_f32 v[106:107], v[170:171], v[106:107] op_sel_hi:[0,1]
	v_pk_mul_f32 v[104:105], v[170:171], v[104:105] op_sel_hi:[0,1]
	v_pk_mul_f32 v[100:101], v[38:39], v[100:101]
	v_pk_mul_f32 v[102:103], v[36:37], v[102:103]
	v_pk_mul_f32 v[96:97], v[34:35], v[96:97]
	v_pk_mul_f32 v[98:99], v[30:31], v[98:99]
	v_pk_mul_f32 v[108:109], v[28:29], v[110:111]
	v_pk_mul_f32 v[104:105], v[26:27], v[104:105]
	s_and_b64 vcc, exec, s[6:7]
	v_pk_mul_f32 v[106:107], v[24:25], v[106:107]
	s_cbranch_vccnz .LBB0_801
	v_mov_b32_e32 v118, v103
	v_mov_b32_e32 v119, v109
	v_mov_b32_e32 v110, v102
	v_mov_b32_e32 v111, v108
	v_pk_mul_f32 v[118:119], v[118:119], v[118:119]
	v_mov_b32_e32 v120, v101
	v_mov_b32_e32 v121, v99
	v_pk_fma_f32 v[110:111], v[110:111], v[110:111], v[118:119]
	v_mov_b32_e32 v118, v100
	v_mov_b32_e32 v119, v98
	v_pk_mul_f32 v[120:121], v[120:121], v[120:121]
	v_mov_b32_e32 v122, v97
	v_pk_fma_f32 v[118:119], v[118:119], v[118:119], v[120:121]
	v_mov_b32_e32 v120, v117
	v_mov_b32_e32 v121, v107
	v_pk_add_f32 v[110:111], v[110:111], v[118:119]
	v_mov_b32_e32 v118, v116
	v_mov_b32_e32 v119, v106
	v_pk_mul_f32 v[120:121], v[120:121], v[120:121]
	v_mov_b32_e32 v123, v105
	v_pk_fma_f32 v[118:119], v[118:119], v[118:119], v[120:121]
	v_mov_b32_e32 v120, v96
	v_mov_b32_e32 v121, v104
	v_pk_mul_f32 v[122:123], v[122:123], v[122:123]
	v_mul_f32_e32 v146, v18, v221
	v_pk_fma_f32 v[120:121], v[120:121], v[120:121], v[122:123]
	v_mul_f32_e32 v124, v16, v221
	v_pk_add_f32 v[118:119], v[118:119], v[120:121]
	v_mul_f32_e32 v120, v22, v221
	v_pk_add_f32 v[110:111], v[110:111], v[118:119]
	v_and_b32_e32 v118, 64, v215
	v_add_f32_e32 v110, v110, v111
	v_xor_b32_e32 v111, 16, v215
	v_add_u32_e32 v118, 64, v118
	v_cmp_lt_i32_e32 vcc, v111, v118
	v_fract_f32_e32 v121, v120
	v_cos_f32_e32 v120, v121
	v_cndmask_b32_e32 v111, v215, v111, vcc
	v_lshlrev_b32_e32 v111, 2, v111
	ds_bpermute_b32 v111, v111, v110
	v_sin_f32_e32 v122, v121
	v_mul_f32_e32 v121, v23, v221
	v_fract_f32_e32 v123, v121
	v_fract_f32_e32 v147, v146
	s_waitcnt lgkmcnt(0)
	v_add_f32_e32 v110, v110, v111
	v_xor_b32_e32 v111, 32, v215
	v_cmp_lt_i32_e32 vcc, v111, v118
	v_cos_f32_e32 v121, v123
	v_sin_f32_e32 v123, v123
	v_cndmask_b32_e32 v111, v215, v111, vcc
	v_lshlrev_b32_e32 v111, 2, v111
	ds_bpermute_b32 v111, v111, v110
	v_fract_f32_e32 v125, v124
	v_cos_f32_e32 v146, v147
	v_sin_f32_e32 v148, v147
	v_mul_f32_e32 v147, v19, v221
	s_waitcnt lgkmcnt(0)
	v_add_f32_e32 v110, v110, v111
	v_fmamk_f32 v110, v110, 0x3c800000, v211
	v_mul_f32_e32 v111, 0x4b800000, v110
	v_cmp_gt_f32_e32 vcc, s84, v110
	v_cos_f32_e32 v124, v125
	v_sin_f32_e32 v126, v125
	v_cndmask_b32_e32 v110, v110, v111, vcc
	v_rsq_f32_e32 v110, v110
	v_mul_f32_e32 v125, v17, v221
	v_fract_f32_e32 v149, v147
	v_fract_f32_e32 v127, v125
	v_mul_f32_e32 v111, 0x45800000, v110
	v_cndmask_b32_e32 v110, v110, v111, vcc
	v_pk_mul_f32 v[102:103], v[102:103], v[110:111] op_sel_hi:[1,0]
	v_pk_mul_f32 v[100:101], v[100:101], v[110:111] op_sel_hi:[1,0]
	v_pk_mul_f32 v[116:117], v[116:117], v[110:111] op_sel_hi:[1,0]
	v_pk_mul_f32 v[96:97], v[96:97], v[110:111] op_sel_hi:[1,0]
	v_pk_mul_f32 v[98:99], v[98:99], v[110:111] op_sel_hi:[1,0]
	v_pk_mul_f32 v[108:109], v[108:109], v[110:111] op_sel_hi:[1,0]
	v_pk_mul_f32 v[104:105], v[104:105], v[110:111] op_sel_hi:[1,0]
	v_pk_mul_f32 v[106:107], v[106:107], v[110:111] op_sel_hi:[1,0]
	v_mul_f32_e32 v110, v20, v221
	v_fract_f32_e32 v111, v110
	v_cos_f32_e32 v110, v111
	v_sin_f32_e32 v118, v111
	v_mul_f32_e32 v111, v21, v221
	v_fract_f32_e32 v119, v111
	v_cos_f32_e32 v111, v119
	v_sin_f32_e32 v119, v119
	v_cos_f32_e32 v147, v149
	v_sin_f32_e32 v149, v149
	v_pk_mul_f32 v[98:99], v[10:11], v[98:99]
	v_cos_f32_e32 v125, v127
	v_sin_f32_e32 v127, v127
	v_pk_mul_f32 v[100:101], v[14:15], v[100:101]
	v_pk_mul_f32 v[108:109], v[8:9], v[108:109]
	v_pk_mul_f32 v[154:155], v[122:123], v[98:99]
	v_pk_mul_f32 v[102:103], v[12:13], v[102:103]
	v_pk_mul_f32 v[104:105], v[2:3], v[104:105]
	v_pk_mul_f32 v[156:157], v[118:119], v[108:109]
	v_pk_fma_f32 v[154:155], v[120:121], v[100:101], v[154:155] neg_lo:[0,0,1] neg_hi:[0,0,1]
	v_pk_mul_f32 v[100:101], v[122:123], v[100:101]
	v_pk_mul_f32 v[96:97], v[6:7], v[96:97]
	v_pk_mul_f32 v[116:117], v[4:5], v[116:117]
	v_pk_mul_f32 v[106:107], v[0:1], v[106:107]
	v_pk_fma_f32 v[156:157], v[110:111], v[102:103], v[156:157] neg_lo:[0,0,1] neg_hi:[0,0,1]
	v_pk_mul_f32 v[102:103], v[118:119], v[102:103]
	v_pk_fma_f32 v[98:99], v[120:121], v[98:99], v[100:101]
	v_pk_mul_f32 v[100:101], v[148:149], v[104:105]
	v_pk_fma_f32 v[108:109], v[110:111], v[108:109], v[102:103]
	v_pk_mul_f32 v[102:103], v[126:127], v[106:107]
	v_pk_fma_f32 v[118:119], v[146:147], v[96:97], v[100:101] neg_lo:[0,0,1] neg_hi:[0,0,1]
	v_pk_mul_f32 v[96:97], v[148:149], v[96:97]
	v_pk_mul_f32 v[100:101], v[126:127], v[116:117]
	v_pk_fma_f32 v[110:111], v[124:125], v[116:117], v[102:103] neg_lo:[0,0,1] neg_hi:[0,0,1]
	v_pk_fma_f32 v[106:107], v[124:125], v[106:107], v[100:101]
	v_pk_fma_f32 v[104:105], v[146:147], v[104:105], v[96:97]
	s_mov_b32 s0, s54
	s_mov_b32 s1, s54
	v_pk_mul_f32 v[100:101], s[0:1], v[154:155]
	v_pk_mul_f32 v[102:103], s[54:55], v[156:157]
	v_pk_mul_f32 v[96:97], s[0:1], v[118:119]
	v_pk_mul_f32 v[116:117], s[54:55], v[110:111]
	v_pk_mul_f32 v[98:99], s[0:1], v[98:99]
	v_pk_mul_f32 v[108:109], s[54:55], v[108:109]
	v_pk_mul_f32 v[104:105], s[0:1], v[104:105]
	v_pk_mul_f32 v[106:107], s[54:55], v[106:107]
; __device__ __forceinline__ float sq4(const f32x4 v) { return (v[0] * v[0] + v[1] * v[1]) + (v[2] * v[2] + v[3] * v[3]); }
; __device__ __forceinline__ u32x4 pack8(const f32x4 a, const f32x4 b) { u32x4 w; w.x = cvt_pk_bf16(a[0], a[1]); w.y = cvt_pk_bf16(a[2], a[3]); w.z = cvt_pk_bf16(b[0], b[1]); w.w = cvt_pk_bf16(b[2], b[3]); return w; }
; __device__ __forceinline__ f32x4 cvti4(const f32x4 a) { typedef int i32x4_ __attribute__((ext_vector_type(4))); const i32x4_ i = __builtin_bit_cast(i32x4_, a); return (f32x4){(float)i[0], (float)i[1], (float)i[2], (float)i[3]}; }
;     __device__ __forceinline__ void operator()(const f32x4 (&acc)[2][2][4][2], const Unit& u, int wr, int wc, int fr, int fq) const {
;     ...
;                 const int row = u.pm * BM + ai * HALF + wr * 64 + m * 16 + fr;
;                 const float r = rr[ai][m];
;                 f32x4 l0 = cvti4(acc[ai][0][m][0]) * r * s0a, l1 = cvti4(acc[ai][0][m][1]) * r * s0b, h0 = cvti4(acc[ai][1][m][0]) * r * s1a, h1 = cvti4(acc[ai][1][m][1]) * r * s1b;
;                 if (mode == 2) {
;                     float ss = (sq4(l0) + sq4(l1)) + (sq4(h0) + sq4(h1));
;                     ss += __shfl_xor(ss, 16); ss += __shfl_xor(ss, 32);
;                     const float rn = rsqrtf(ss * (1.f / 64.f) + EPS);
;                     l0 = l0 * rn * g0a; l1 = l1 * rn * g0b; h0 = h0 * rn * g1a; h1 = h1 * rn * g1b;
;                     f32x4 c0, c1, s0, s1; rope_cs(pf[ai][m], fr0, c0, s0); rope_cs(pf[ai][m], fr1, c1, s1);
;                     const f32x4 nl0 = l0 * c0 - h0 * s0, nh0 = h0 * c0 + l0 * s0, nl1 = l1 * c1 - h1 * s1, nh1 = h1 * c1 + l1 * s1;
;                     l0 = nl0 * scale; l1 = nl1 * scale; h0 = nh0 * scale; h1 = nh1 * scale;
;                 }
;                 bf16_t* p = dst + (size_t)row * pitch + coff + d0;
;                 st16_wt(p, pack8(l0, l1));
;                 st16_wt((p + 32), pack8(h0, h1));
.LBB0_801:
	v_lshlrev_b64 v[110:111], 10, v[152:153]
	v_lshl_add_u64 v[110:111], v[94:95], 0, v[110:111]
	v_cvt_pk_bf16_f32 v118, v102, v103
	v_cvt_pk_bf16_f32 v119, v100, v101
	v_cvt_pk_bf16_f32 v120, v116, v117
	v_cvt_pk_bf16_f32 v121, v96, v97
	global_store_dwordx4 v[110:111], v[118:121], off sc1
	v_cvt_pk_bf16_f32 v96, v108, v109
	v_cvt_pk_bf16_f32 v97, v98, v99
	v_pk_mul_f32 v[76:77], v[150:151], v[76:77] op_sel_hi:[0,1]
	v_cvt_pk_bf16_f32 v98, v106, v107
	v_cvt_pk_bf16_f32 v99, v104, v105
	global_store_dwordx4 v[110:111], v[96:99], off offset:64 sc1
	v_pk_mul_f32 v[80:81], v[150:151], v[80:81] op_sel_hi:[0,1]
	v_pk_mul_f32 v[78:79], v[150:151], v[78:79] op_sel_hi:[0,1]
	v_pk_mul_f32 v[74:75], v[150:151], v[74:75] op_sel_hi:[0,1]
	v_pk_mul_f32 v[96:97], v[32:33], v[76:77]
	v_pk_mul_f32 v[88:89], v[150:151], v[88:89] op_sel_hi:[0,1]
	v_pk_mul_f32 v[76:77], v[150:151], v[86:87] op_sel_hi:[0,1]
	v_pk_mul_f32 v[84:85], v[150:151], v[84:85] op_sel_hi:[0,1]
	v_pk_mul_f32 v[82:83], v[150:151], v[82:83] op_sel_hi:[0,1]
	v_pk_mul_f32 v[78:79], v[38:39], v[78:79]
	v_pk_mul_f32 v[80:81], v[36:37], v[80:81]
	v_pk_mul_f32 v[74:75], v[34:35], v[74:75]
	v_pk_mul_f32 v[76:77], v[30:31], v[76:77]
	v_pk_mul_f32 v[86:87], v[28:29], v[88:89]
	v_pk_mul_f32 v[82:83], v[26:27], v[82:83]
	s_and_b64 vcc, exec, s[6:7]
	v_pk_mul_f32 v[84:85], v[24:25], v[84:85]
	s_cbranch_vccnz .LBB0_803
	v_mov_b32_e32 v98, v81
	v_mov_b32_e32 v99, v87
	v_mov_b32_e32 v88, v80
	v_mov_b32_e32 v89, v86
	v_pk_mul_f32 v[98:99], v[98:99], v[98:99]
	v_mov_b32_e32 v100, v79
	v_mov_b32_e32 v101, v77
	v_pk_fma_f32 v[88:89], v[88:89], v[88:89], v[98:99]
	v_mov_b32_e32 v98, v78
	v_mov_b32_e32 v99, v76
	v_pk_mul_f32 v[100:101], v[100:101], v[100:101]
	v_mov_b32_e32 v102, v75
	v_pk_fma_f32 v[98:99], v[98:99], v[98:99], v[100:101]
	v_mov_b32_e32 v100, v97
	v_mov_b32_e32 v101, v85
	v_pk_add_f32 v[88:89], v[88:89], v[98:99]
	v_mov_b32_e32 v98, v96
	v_mov_b32_e32 v99, v84
	v_pk_mul_f32 v[100:101], v[100:101], v[100:101]
	v_mov_b32_e32 v103, v83
	v_pk_fma_f32 v[98:99], v[98:99], v[98:99], v[100:101]
	v_mov_b32_e32 v100, v74
	v_mov_b32_e32 v101, v82
	v_pk_mul_f32 v[102:103], v[102:103], v[102:103]
	v_mul_f32_e32 v108, v18, v220
	v_pk_fma_f32 v[100:101], v[100:101], v[100:101], v[102:103]
	v_mul_f32_e32 v104, v16, v220
	v_pk_add_f32 v[98:99], v[98:99], v[100:101]
	v_mul_f32_e32 v100, v22, v220
	v_pk_add_f32 v[88:89], v[88:89], v[98:99]
	v_and_b32_e32 v98, 64, v215
	v_add_f32_e32 v88, v88, v89
	v_xor_b32_e32 v89, 16, v215
	v_add_u32_e32 v98, 64, v98
	v_cmp_lt_i32_e32 vcc, v89, v98
	v_fract_f32_e32 v101, v100
	v_cos_f32_e32 v100, v101
	v_cndmask_b32_e32 v89, v215, v89, vcc
	v_lshlrev_b32_e32 v89, 2, v89
	ds_bpermute_b32 v89, v89, v88
	v_sin_f32_e32 v102, v101
	v_mul_f32_e32 v101, v23, v220
	v_fract_f32_e32 v103, v101
	v_fract_f32_e32 v109, v108
	s_waitcnt lgkmcnt(0)
	v_add_f32_e32 v88, v88, v89
	v_xor_b32_e32 v89, 32, v215
	v_cmp_lt_i32_e32 vcc, v89, v98
	v_cos_f32_e32 v101, v103
	v_sin_f32_e32 v103, v103
	v_cndmask_b32_e32 v89, v215, v89, vcc
	v_lshlrev_b32_e32 v89, 2, v89
	ds_bpermute_b32 v89, v89, v88
	v_fract_f32_e32 v105, v104
	v_cos_f32_e32 v108, v109
	v_sin_f32_e32 v110, v109
	v_mul_f32_e32 v109, v19, v220
	s_waitcnt lgkmcnt(0)
	v_add_f32_e32 v88, v88, v89
	v_fmamk_f32 v88, v88, 0x3c800000, v211
	v_mul_f32_e32 v89, 0x4b800000, v88
	v_cmp_gt_f32_e32 vcc, s84, v88
	v_cos_f32_e32 v104, v105
	v_sin_f32_e32 v106, v105
	v_cndmask_b32_e32 v88, v88, v89, vcc
	v_rsq_f32_e32 v88, v88
	v_mul_f32_e32 v105, v17, v220
	v_fract_f32_e32 v111, v109
	v_fract_f32_e32 v107, v105
	v_mul_f32_e32 v89, 0x45800000, v88
	v_cndmask_b32_e32 v88, v88, v89, vcc
	v_pk_mul_f32 v[80:81], v[80:81], v[88:89] op_sel_hi:[1,0]
	v_pk_mul_f32 v[78:79], v[78:79], v[88:89] op_sel_hi:[1,0]
	v_pk_mul_f32 v[96:97], v[96:97], v[88:89] op_sel_hi:[1,0]
	v_pk_mul_f32 v[74:75], v[74:75], v[88:89] op_sel_hi:[1,0]
	v_pk_mul_f32 v[76:77], v[76:77], v[88:89] op_sel_hi:[1,0]
	v_pk_mul_f32 v[86:87], v[86:87], v[88:89] op_sel_hi:[1,0]
	v_pk_mul_f32 v[82:83], v[82:83], v[88:89] op_sel_hi:[1,0]
	v_pk_mul_f32 v[84:85], v[84:85], v[88:89] op_sel_hi:[1,0]
	v_mul_f32_e32 v88, v20, v220
	v_fract_f32_e32 v89, v88
	v_cos_f32_e32 v88, v89
	v_sin_f32_e32 v98, v89
	v_mul_f32_e32 v89, v21, v220
	v_fract_f32_e32 v99, v89
	v_cos_f32_e32 v89, v99
	v_sin_f32_e32 v99, v99
	v_cos_f32_e32 v109, v111
	v_sin_f32_e32 v111, v111
	v_pk_mul_f32 v[76:77], v[10:11], v[76:77]
	v_cos_f32_e32 v105, v107
	v_sin_f32_e32 v107, v107
	v_pk_mul_f32 v[78:79], v[14:15], v[78:79]
	v_pk_mul_f32 v[86:87], v[8:9], v[86:87]
	v_pk_mul_f32 v[116:117], v[102:103], v[76:77]
	v_pk_mul_f32 v[80:81], v[12:13], v[80:81]
	v_pk_mul_f32 v[82:83], v[2:3], v[82:83]
	v_pk_mul_f32 v[118:119], v[98:99], v[86:87]
	v_pk_fma_f32 v[116:117], v[100:101], v[78:79], v[116:117] neg_lo:[0,0,1] neg_hi:[0,0,1]
	v_pk_mul_f32 v[78:79], v[102:103], v[78:79]
	v_pk_mul_f32 v[74:75], v[6:7], v[74:75]
	v_pk_mul_f32 v[96:97], v[4:5], v[96:97]
	v_pk_mul_f32 v[84:85], v[0:1], v[84:85]
	v_pk_fma_f32 v[118:119], v[88:89], v[80:81], v[118:119] neg_lo:[0,0,1] neg_hi:[0,0,1]
	v_pk_mul_f32 v[80:81], v[98:99], v[80:81]
	v_pk_fma_f32 v[76:77], v[100:101], v[76:77], v[78:79]
	v_pk_mul_f32 v[78:79], v[110:111], v[82:83]
	v_pk_fma_f32 v[86:87], v[88:89], v[86:87], v[80:81]
	v_pk_mul_f32 v[80:81], v[106:107], v[84:85]
	v_pk_fma_f32 v[98:99], v[108:109], v[74:75], v[78:79] neg_lo:[0,0,1] neg_hi:[0,0,1]
	v_pk_mul_f32 v[74:75], v[110:111], v[74:75]
	v_pk_mul_f32 v[78:79], v[106:107], v[96:97]
	v_pk_fma_f32 v[88:89], v[104:105], v[96:97], v[80:81] neg_lo:[0,0,1] neg_hi:[0,0,1]
	v_pk_fma_f32 v[84:85], v[104:105], v[84:85], v[78:79]
	v_pk_fma_f32 v[82:83], v[108:109], v[82:83], v[74:75]
	s_mov_b32 s0, s54
	s_mov_b32 s1, s54
	v_pk_mul_f32 v[78:79], s[0:1], v[116:117]
	v_pk_mul_f32 v[80:81], s[54:55], v[118:119]
	v_pk_mul_f32 v[74:75], s[0:1], v[98:99]
	v_pk_mul_f32 v[96:97], s[54:55], v[88:89]
	v_pk_mul_f32 v[76:77], s[0:1], v[76:77]
	v_pk_mul_f32 v[86:87], s[54:55], v[86:87]
	v_pk_mul_f32 v[82:83], s[0:1], v[82:83]
	v_pk_mul_f32 v[84:85], s[54:55], v[84:85]
; __device__ __forceinline__ float sq4(const f32x4 v) { return (v[0] * v[0] + v[1] * v[1]) + (v[2] * v[2] + v[3] * v[3]); }
; __device__ __forceinline__ u32x4 pack8(const f32x4 a, const f32x4 b) { u32x4 w; w.x = cvt_pk_bf16(a[0], a[1]); w.y = cvt_pk_bf16(a[2], a[3]); w.z = cvt_pk_bf16(b[0], b[1]); w.w = cvt_pk_bf16(b[2], b[3]); return w; }
; __device__ __forceinline__ f32x4 cvti4(const f32x4 a) { typedef int i32x4_ __attribute__((ext_vector_type(4))); const i32x4_ i = __builtin_bit_cast(i32x4_, a); return (f32x4){(float)i[0], (float)i[1], (float)i[2], (float)i[3]}; }
;     __device__ __forceinline__ void operator()(const f32x4 (&acc)[2][2][4][2], const Unit& u, int wr, int wc, int fr, int fq) const {
;     ...
;                 const int row = u.pm * BM + ai * HALF + wr * 64 + m * 16 + fr;
;                 const float r = rr[ai][m];
;                 f32x4 l0 = cvti4(acc[ai][0][m][0]) * r * s0a, l1 = cvti4(acc[ai][0][m][1]) * r * s0b, h0 = cvti4(acc[ai][1][m][0]) * r * s1a, h1 = cvti4(acc[ai][1][m][1]) * r * s1b;
;                 if (mode == 2) {
;                     float ss = (sq4(l0) + sq4(l1)) + (sq4(h0) + sq4(h1));
;                     ss += __shfl_xor(ss, 16); ss += __shfl_xor(ss, 32);
;                     const float rn = rsqrtf(ss * (1.f / 64.f) + EPS);
;                     l0 = l0 * rn * g0a; l1 = l1 * rn * g0b; h0 = h0 * rn * g1a; h1 = h1 * rn * g1b;
;                     f32x4 c0, c1, s0, s1; rope_cs(pf[ai][m], fr0, c0, s0); rope_cs(pf[ai][m], fr1, c1, s1);
;                     const f32x4 nl0 = l0 * c0 - h0 * s0, nh0 = h0 * c0 + l0 * s0, nl1 = l1 * c1 - h1 * s1, nh1 = h1 * c1 + l1 * s1;
;                     l0 = nl0 * scale; l1 = nl1 * scale; h0 = nh0 * scale; h1 = nh1 * scale;
;                 }
;                 bf16_t* p = dst + (size_t)row * pitch + coff + d0;
;                 st16_wt(p, pack8(l0, l1));
;                 st16_wt((p + 32), pack8(h0, h1));
.LBB0_803:
	v_lshlrev_b64 v[88:89], 10, v[114:115]
	v_lshl_add_u64 v[88:89], v[94:95], 0, v[88:89]
	v_cvt_pk_bf16_f32 v98, v80, v81
	v_cvt_pk_bf16_f32 v99, v78, v79
	v_cvt_pk_bf16_f32 v100, v96, v97
	v_cvt_pk_bf16_f32 v101, v74, v75
	global_store_dwordx4 v[88:89], v[98:101], off sc1
	v_cvt_pk_bf16_f32 v74, v86, v87
	v_cvt_pk_bf16_f32 v75, v76, v77
	v_pk_mul_f32 v[58:59], v[112:113], v[58:59] op_sel_hi:[0,1]
	v_cvt_pk_bf16_f32 v76, v84, v85
	v_cvt_pk_bf16_f32 v77, v82, v83
	global_store_dwordx4 v[88:89], v[74:77], off offset:64 sc1
	v_pk_mul_f32 v[62:63], v[112:113], v[62:63] op_sel_hi:[0,1]
	v_pk_mul_f32 v[60:61], v[112:113], v[60:61] op_sel_hi:[0,1]
	v_pk_mul_f32 v[56:57], v[112:113], v[56:57] op_sel_hi:[0,1]
	v_pk_mul_f32 v[74:75], v[32:33], v[58:59]
	v_pk_mul_f32 v[70:71], v[112:113], v[70:71] op_sel_hi:[0,1]
	v_pk_mul_f32 v[58:59], v[112:113], v[68:69] op_sel_hi:[0,1]
	v_pk_mul_f32 v[66:67], v[112:113], v[66:67] op_sel_hi:[0,1]
	v_pk_mul_f32 v[64:65], v[112:113], v[64:65] op_sel_hi:[0,1]
	v_pk_mul_f32 v[60:61], v[38:39], v[60:61]
	v_pk_mul_f32 v[62:63], v[36:37], v[62:63]
	v_pk_mul_f32 v[56:57], v[34:35], v[56:57]
	v_pk_mul_f32 v[58:59], v[30:31], v[58:59]
	v_pk_mul_f32 v[68:69], v[28:29], v[70:71]
	v_pk_mul_f32 v[64:65], v[26:27], v[64:65]
	s_and_b64 vcc, exec, s[6:7]
	v_pk_mul_f32 v[66:67], v[24:25], v[66:67]
	s_cbranch_vccnz .LBB0_805
	v_mov_b32_e32 v76, v63
	v_mov_b32_e32 v77, v69
	v_mov_b32_e32 v70, v62
	v_mov_b32_e32 v71, v68
	v_pk_mul_f32 v[76:77], v[76:77], v[76:77]
	v_mov_b32_e32 v78, v61
	v_mov_b32_e32 v79, v59
	v_pk_fma_f32 v[70:71], v[70:71], v[70:71], v[76:77]
	v_mov_b32_e32 v76, v60
	v_mov_b32_e32 v77, v58
	v_pk_mul_f32 v[78:79], v[78:79], v[78:79]
	v_mov_b32_e32 v80, v57
	v_pk_fma_f32 v[76:77], v[76:77], v[76:77], v[78:79]
	v_mov_b32_e32 v78, v75
	v_mov_b32_e32 v79, v67
	v_pk_add_f32 v[70:71], v[70:71], v[76:77]
	v_mov_b32_e32 v76, v74
	v_mov_b32_e32 v77, v66
	v_pk_mul_f32 v[78:79], v[78:79], v[78:79]
	v_mov_b32_e32 v81, v65
	v_pk_fma_f32 v[76:77], v[76:77], v[76:77], v[78:79]
	v_mov_b32_e32 v78, v56
	v_mov_b32_e32 v79, v64
	v_pk_mul_f32 v[80:81], v[80:81], v[80:81]
	v_mul_f32_e32 v86, v18, v113
	v_pk_fma_f32 v[78:79], v[78:79], v[78:79], v[80:81]
	v_mul_f32_e32 v82, v16, v113
	v_pk_add_f32 v[76:77], v[76:77], v[78:79]
	v_mul_f32_e32 v78, v22, v113
	v_pk_add_f32 v[70:71], v[70:71], v[76:77]
	v_and_b32_e32 v76, 64, v215
	v_add_f32_e32 v70, v70, v71
	v_xor_b32_e32 v71, 16, v215
	v_add_u32_e32 v76, 64, v76
	v_cmp_lt_i32_e32 vcc, v71, v76
	v_fract_f32_e32 v79, v78
	v_cos_f32_e32 v78, v79
	v_cndmask_b32_e32 v71, v215, v71, vcc
	v_lshlrev_b32_e32 v71, 2, v71
	ds_bpermute_b32 v71, v71, v70
	v_sin_f32_e32 v80, v79
	v_mul_f32_e32 v79, v23, v113
	v_fract_f32_e32 v81, v79
	v_fract_f32_e32 v87, v86
	s_waitcnt lgkmcnt(0)
	v_add_f32_e32 v70, v70, v71
	v_xor_b32_e32 v71, 32, v215
	v_cmp_lt_i32_e32 vcc, v71, v76
	v_cos_f32_e32 v79, v81
	v_sin_f32_e32 v81, v81
	v_cndmask_b32_e32 v71, v215, v71, vcc
	v_lshlrev_b32_e32 v71, 2, v71
	ds_bpermute_b32 v71, v71, v70
	v_fract_f32_e32 v83, v82
	v_cos_f32_e32 v86, v87
	v_sin_f32_e32 v88, v87
	v_mul_f32_e32 v87, v19, v113
	s_waitcnt lgkmcnt(0)
	v_add_f32_e32 v70, v70, v71
	v_fmamk_f32 v70, v70, 0x3c800000, v211
	v_mul_f32_e32 v71, 0x4b800000, v70
	v_cmp_gt_f32_e32 vcc, s84, v70
	v_cos_f32_e32 v82, v83
	v_sin_f32_e32 v84, v83
	v_cndmask_b32_e32 v70, v70, v71, vcc
	v_rsq_f32_e32 v70, v70
	v_mul_f32_e32 v83, v17, v113
	v_fract_f32_e32 v89, v87
	v_fract_f32_e32 v85, v83
	v_mul_f32_e32 v71, 0x45800000, v70
	v_cndmask_b32_e32 v70, v70, v71, vcc
	v_pk_mul_f32 v[62:63], v[62:63], v[70:71] op_sel_hi:[1,0]
	v_pk_mul_f32 v[60:61], v[60:61], v[70:71] op_sel_hi:[1,0]
	v_pk_mul_f32 v[74:75], v[74:75], v[70:71] op_sel_hi:[1,0]
	v_pk_mul_f32 v[56:57], v[56:57], v[70:71] op_sel_hi:[1,0]
	v_pk_mul_f32 v[58:59], v[58:59], v[70:71] op_sel_hi:[1,0]
	v_pk_mul_f32 v[68:69], v[68:69], v[70:71] op_sel_hi:[1,0]
	v_pk_mul_f32 v[64:65], v[64:65], v[70:71] op_sel_hi:[1,0]
	v_pk_mul_f32 v[66:67], v[66:67], v[70:71] op_sel_hi:[1,0]
	v_mul_f32_e32 v70, v20, v113
	v_fract_f32_e32 v71, v70
	v_cos_f32_e32 v70, v71
	v_sin_f32_e32 v76, v71
	v_mul_f32_e32 v71, v21, v113
	v_fract_f32_e32 v77, v71
	v_cos_f32_e32 v71, v77
	v_sin_f32_e32 v77, v77
	v_cos_f32_e32 v87, v89
	v_sin_f32_e32 v89, v89
	v_pk_mul_f32 v[58:59], v[10:11], v[58:59]
	v_cos_f32_e32 v83, v85
	v_sin_f32_e32 v85, v85
	v_pk_mul_f32 v[60:61], v[14:15], v[60:61]
	v_pk_mul_f32 v[68:69], v[8:9], v[68:69]
	v_pk_mul_f32 v[96:97], v[80:81], v[58:59]
	v_pk_mul_f32 v[62:63], v[12:13], v[62:63]
	v_pk_mul_f32 v[64:65], v[2:3], v[64:65]
	v_pk_mul_f32 v[98:99], v[76:77], v[68:69]
	v_pk_fma_f32 v[96:97], v[78:79], v[60:61], v[96:97] neg_lo:[0,0,1] neg_hi:[0,0,1]
	v_pk_mul_f32 v[60:61], v[80:81], v[60:61]
	v_pk_mul_f32 v[56:57], v[6:7], v[56:57]
	v_pk_mul_f32 v[74:75], v[4:5], v[74:75]
	v_pk_mul_f32 v[66:67], v[0:1], v[66:67]
	v_pk_fma_f32 v[98:99], v[70:71], v[62:63], v[98:99] neg_lo:[0,0,1] neg_hi:[0,0,1]
	v_pk_mul_f32 v[62:63], v[76:77], v[62:63]
	v_pk_fma_f32 v[58:59], v[78:79], v[58:59], v[60:61]
	v_pk_mul_f32 v[60:61], v[88:89], v[64:65]
	v_pk_fma_f32 v[68:69], v[70:71], v[68:69], v[62:63]
	v_pk_mul_f32 v[62:63], v[84:85], v[66:67]
	v_pk_fma_f32 v[76:77], v[86:87], v[56:57], v[60:61] neg_lo:[0,0,1] neg_hi:[0,0,1]
	v_pk_mul_f32 v[56:57], v[88:89], v[56:57]
	v_pk_mul_f32 v[60:61], v[84:85], v[74:75]
	v_pk_fma_f32 v[70:71], v[82:83], v[74:75], v[62:63] neg_lo:[0,0,1] neg_hi:[0,0,1]
	v_pk_fma_f32 v[66:67], v[82:83], v[66:67], v[60:61]
	v_pk_fma_f32 v[64:65], v[86:87], v[64:65], v[56:57]
	s_mov_b32 s0, s54
	s_mov_b32 s1, s54
	v_pk_mul_f32 v[60:61], s[0:1], v[96:97]
	v_pk_mul_f32 v[62:63], s[54:55], v[98:99]
	v_pk_mul_f32 v[56:57], s[0:1], v[76:77]
	v_pk_mul_f32 v[74:75], s[54:55], v[70:71]
	v_pk_mul_f32 v[58:59], s[0:1], v[58:59]
	v_pk_mul_f32 v[68:69], s[54:55], v[68:69]
	v_pk_mul_f32 v[64:65], s[0:1], v[64:65]
	v_pk_mul_f32 v[66:67], s[54:55], v[66:67]
; __device__ __forceinline__ float sq4(const f32x4 v) { return (v[0] * v[0] + v[1] * v[1]) + (v[2] * v[2] + v[3] * v[3]); }
; __device__ __forceinline__ u32x4 pack8(const f32x4 a, const f32x4 b) { u32x4 w; w.x = cvt_pk_bf16(a[0], a[1]); w.y = cvt_pk_bf16(a[2], a[3]); w.z = cvt_pk_bf16(b[0], b[1]); w.w = cvt_pk_bf16(b[2], b[3]); return w; }
; __device__ __forceinline__ f32x4 cvti4(const f32x4 a) { typedef int i32x4_ __attribute__((ext_vector_type(4))); const i32x4_ i = __builtin_bit_cast(i32x4_, a); return (f32x4){(float)i[0], (float)i[1], (float)i[2], (float)i[3]}; }
; #define PG8_BAR __builtin_amdgcn_s_barrier()
;     __device__ __forceinline__ void operator()(const f32x4 (&acc)[2][2][4][2], const Unit& u, int wr, int wc, int fr, int fq) const {
;     ...
;                 const int row = u.pm * BM + ai * HALF + wr * 64 + m * 16 + fr;
;                 const float r = rr[ai][m];
;                 f32x4 l0 = cvti4(acc[ai][0][m][0]) * r * s0a, l1 = cvti4(acc[ai][0][m][1]) * r * s0b, h0 = cvti4(acc[ai][1][m][0]) * r * s1a, h1 = cvti4(acc[ai][1][m][1]) * r * s1b;
;                 if (mode == 2) {
;                     float ss = (sq4(l0) + sq4(l1)) + (sq4(h0) + sq4(h1));
;                     ss += __shfl_xor(ss, 16); ss += __shfl_xor(ss, 32);
;                     const float rn = rsqrtf(ss * (1.f / 64.f) + EPS);
;                     l0 = l0 * rn * g0a; l1 = l1 * rn * g0b; h0 = h0 * rn * g1a; h1 = h1 * rn * g1b;
;                     f32x4 c0, c1, s0, s1; rope_cs(pf[ai][m], fr0, c0, s0); rope_cs(pf[ai][m], fr1, c1, s1);
;                     const f32x4 nl0 = l0 * c0 - h0 * s0, nh0 = h0 * c0 + l0 * s0, nl1 = l1 * c1 - h1 * s1, nh1 = h1 * c1 + l1 * s1;
;                     l0 = nl0 * scale; l1 = nl1 * scale; h0 = nh0 * scale; h1 = nh1 * scale;
;                 }
;                 bf16_t* p = dst + (size_t)row * pitch + coff + d0;
;                 st16_wt(p, pack8(l0, l1));
;                 st16_wt((p + 32), pack8(h0, h1));
;     ...
;         if (!has_next) break;
; #pragma unroll
;         for (int a = 0; a < 2; ++a)
; #pragma unroll
;             for (int b = 0; b < 2; ++b)
; #pragma unroll
;                 for (int m = 0; m < 4; ++m)
; #pragma unroll
;                     for (int n = 0; n < 2; ++n) acc[a][b][m][n] = (f32x4){0.f, 0.f, 0.f, 0.f};
;         cur = nxt; cA = nA; cB = nB; ++ui;
;         if constexpr (ALIGN_EPI) { if (wr == 1) PG8_BAR; }
.LBB0_805:
	v_pk_mul_f32 v[42:43], v[90:91], v[42:43] op_sel_hi:[0,1]
	v_pk_mul_f32 v[40:41], v[90:91], v[40:41] op_sel_hi:[0,1]
	v_pk_mul_f32 v[34:35], v[34:35], v[40:41]
	v_pk_mul_f32 v[32:33], v[32:33], v[42:43]
	v_pk_mul_f32 v[40:41], v[90:91], v[54:55] op_sel_hi:[0,1]
	v_pk_mul_f32 v[42:43], v[90:91], v[52:53] op_sel_hi:[0,1]
	v_lshlrev_b64 v[70:71], 10, v[92:93]
	v_pk_mul_f32 v[46:47], v[90:91], v[46:47] op_sel_hi:[0,1]
	v_pk_mul_f32 v[44:45], v[90:91], v[44:45] op_sel_hi:[0,1]
	v_pk_mul_f32 v[30:31], v[30:31], v[42:43]
	v_pk_mul_f32 v[28:29], v[28:29], v[40:41]
	v_pk_mul_f32 v[40:41], v[90:91], v[50:51] op_sel_hi:[0,1]
	v_pk_mul_f32 v[42:43], v[90:91], v[48:49] op_sel_hi:[0,1]
	v_lshl_add_u64 v[70:71], v[94:95], 0, v[70:71]
	v_pk_mul_f32 v[38:39], v[38:39], v[44:45]
	v_pk_mul_f32 v[36:37], v[36:37], v[46:47]
	v_pk_mul_f32 v[26:27], v[26:27], v[42:43]
	s_and_b64 vcc, exec, s[6:7]
	v_pk_mul_f32 v[24:25], v[24:25], v[40:41]
	v_cvt_pk_bf16_f32 v76, v62, v63
	v_cvt_pk_bf16_f32 v77, v60, v61
	v_cvt_pk_bf16_f32 v78, v74, v75
	v_cvt_pk_bf16_f32 v79, v56, v57
	global_store_dwordx4 v[70:71], v[76:79], off sc1
	v_cvt_pk_bf16_f32 v56, v68, v69
	v_cvt_pk_bf16_f32 v57, v58, v59
	v_cvt_pk_bf16_f32 v58, v66, v67
	v_cvt_pk_bf16_f32 v59, v64, v65
	global_store_dwordx4 v[70:71], v[56:59], off offset:64 sc1
	s_cbranch_vccnz .LBB0_807
	v_mov_b32_e32 v42, v37
	v_mov_b32_e32 v43, v29
	v_mov_b32_e32 v40, v36
	v_mov_b32_e32 v41, v28
	v_pk_mul_f32 v[42:43], v[42:43], v[42:43]
	v_mov_b32_e32 v44, v39
	v_mov_b32_e32 v45, v31
	v_pk_fma_f32 v[40:41], v[40:41], v[40:41], v[42:43]
	v_mov_b32_e32 v42, v38
	v_mov_b32_e32 v43, v30
	v_pk_mul_f32 v[44:45], v[44:45], v[44:45]
	v_mov_b32_e32 v46, v35
	v_pk_fma_f32 v[42:43], v[42:43], v[42:43], v[44:45]
	v_mov_b32_e32 v44, v33
	v_mov_b32_e32 v45, v25
	v_pk_add_f32 v[40:41], v[40:41], v[42:43]
	v_mov_b32_e32 v42, v32
	v_mov_b32_e32 v43, v24
	v_pk_mul_f32 v[44:45], v[44:45], v[44:45]
	v_mov_b32_e32 v47, v27
	v_pk_fma_f32 v[42:43], v[42:43], v[42:43], v[44:45]
	v_mov_b32_e32 v44, v34
	v_mov_b32_e32 v45, v26
	v_pk_mul_f32 v[46:47], v[46:47], v[46:47]
	v_mul_f32_e32 v20, v20, v91
	v_pk_fma_f32 v[44:45], v[44:45], v[44:45], v[46:47]
	v_mul_f32_e32 v21, v21, v91
	v_pk_add_f32 v[42:43], v[42:43], v[44:45]
	v_mul_f32_e32 v22, v22, v91
	v_pk_add_f32 v[40:41], v[40:41], v[42:43]
	v_and_b32_e32 v42, 64, v215
	v_add_f32_e32 v40, v40, v41
	v_xor_b32_e32 v41, 16, v215
	v_add_u32_e32 v42, 64, v42
	v_cmp_lt_i32_e32 vcc, v41, v42
	v_mul_f32_e32 v23, v23, v91
	v_mul_f32_e32 v16, v16, v91
	v_cndmask_b32_e32 v41, v215, v41, vcc
	v_lshlrev_b32_e32 v41, 2, v41
	ds_bpermute_b32 v41, v41, v40
	v_mul_f32_e32 v17, v17, v91
	v_mul_f32_e32 v18, v18, v91
	v_mul_f32_e32 v19, v19, v91
	s_mov_b32 s0, s54
	s_waitcnt lgkmcnt(0)
	v_add_f32_e32 v40, v40, v41
	v_xor_b32_e32 v41, 32, v215
	v_cmp_lt_i32_e32 vcc, v41, v42
	s_mov_b32 s1, s54
	s_nop 0
	v_cndmask_b32_e32 v41, v215, v41, vcc
	v_lshlrev_b32_e32 v41, 2, v41
	ds_bpermute_b32 v41, v41, v40
	s_waitcnt lgkmcnt(0)
	v_add_f32_e32 v40, v40, v41
	v_fmamk_f32 v40, v40, 0x3c800000, v211
	v_mul_f32_e32 v41, 0x4b800000, v40
	v_cmp_gt_f32_e32 vcc, s84, v40
	s_nop 1
	v_cndmask_b32_e32 v40, v40, v41, vcc
	v_rsq_f32_e32 v40, v40
	s_nop 0
	v_mul_f32_e32 v41, 0x45800000, v40
	v_cndmask_b32_e32 v40, v40, v41, vcc
	v_pk_mul_f32 v[26:27], v[26:27], v[40:41] op_sel_hi:[1,0]
	v_pk_mul_f32 v[24:25], v[24:25], v[40:41] op_sel_hi:[1,0]
	v_pk_mul_f32 v[2:3], v[2:3], v[26:27]
	v_pk_mul_f32 v[0:1], v[0:1], v[24:25]
	v_fract_f32_e32 v24, v20
	v_fract_f32_e32 v25, v21
	v_fract_f32_e32 v26, v22
	v_fract_f32_e32 v27, v23
	v_pk_mul_f32 v[30:31], v[30:31], v[40:41] op_sel_hi:[1,0]
	v_pk_mul_f32 v[28:29], v[28:29], v[40:41] op_sel_hi:[1,0]
	v_cos_f32_e32 v20, v24
	v_sin_f32_e32 v24, v24
	v_cos_f32_e32 v21, v25
	v_sin_f32_e32 v25, v25
	v_cos_f32_e32 v22, v26
	v_sin_f32_e32 v26, v26
	v_cos_f32_e32 v23, v27
	v_sin_f32_e32 v27, v27
	v_pk_mul_f32 v[8:9], v[8:9], v[28:29]
	v_pk_mul_f32 v[10:11], v[10:11], v[30:31]
	v_fract_f32_e32 v28, v16
	v_fract_f32_e32 v29, v17
	v_fract_f32_e32 v30, v18
	v_fract_f32_e32 v31, v19
	v_cos_f32_e32 v16, v28
	v_sin_f32_e32 v28, v28
	v_cos_f32_e32 v17, v29
	v_sin_f32_e32 v29, v29
	v_cos_f32_e32 v18, v30
	v_sin_f32_e32 v30, v30
	v_cos_f32_e32 v19, v31
	v_sin_f32_e32 v31, v31
	v_pk_mul_f32 v[36:37], v[36:37], v[40:41] op_sel_hi:[1,0]
	v_pk_mul_f32 v[38:39], v[38:39], v[40:41] op_sel_hi:[1,0]
	v_pk_mul_f32 v[32:33], v[32:33], v[40:41] op_sel_hi:[1,0]
	v_pk_mul_f32 v[34:35], v[34:35], v[40:41] op_sel_hi:[1,0]
	v_pk_mul_f32 v[14:15], v[14:15], v[38:39]
	v_pk_mul_f32 v[12:13], v[12:13], v[36:37]
	v_pk_mul_f32 v[6:7], v[6:7], v[34:35]
	v_pk_mul_f32 v[4:5], v[4:5], v[32:33]
	v_pk_mul_f32 v[32:33], v[26:27], v[10:11]
	v_pk_mul_f32 v[34:35], v[24:25], v[8:9]
	v_pk_fma_f32 v[32:33], v[22:23], v[14:15], v[32:33] neg_lo:[0,0,1] neg_hi:[0,0,1]
	v_pk_fma_f32 v[34:35], v[20:21], v[12:13], v[34:35] neg_lo:[0,0,1] neg_hi:[0,0,1]
	v_pk_mul_f32 v[14:15], v[26:27], v[14:15]
	v_pk_mul_f32 v[12:13], v[24:25], v[12:13]
	v_pk_fma_f32 v[10:11], v[22:23], v[10:11], v[14:15]
	v_pk_fma_f32 v[8:9], v[20:21], v[8:9], v[12:13]
	v_pk_mul_f32 v[12:13], v[30:31], v[2:3]
	v_pk_mul_f32 v[14:15], v[28:29], v[0:1]
	v_pk_fma_f32 v[12:13], v[18:19], v[6:7], v[12:13] neg_lo:[0,0,1] neg_hi:[0,0,1]
	v_pk_fma_f32 v[14:15], v[16:17], v[4:5], v[14:15] neg_lo:[0,0,1] neg_hi:[0,0,1]
	v_pk_mul_f32 v[6:7], v[30:31], v[6:7]
	v_pk_mul_f32 v[4:5], v[28:29], v[4:5]
	v_pk_fma_f32 v[2:3], v[18:19], v[2:3], v[6:7]
	v_pk_fma_f32 v[0:1], v[16:17], v[0:1], v[4:5]
	v_pk_mul_f32 v[38:39], s[0:1], v[32:33]
	v_pk_mul_f32 v[36:37], s[54:55], v[34:35]
	v_pk_mul_f32 v[34:35], s[0:1], v[12:13]
	v_pk_mul_f32 v[32:33], s[54:55], v[14:15]
	v_pk_mul_f32 v[30:31], s[0:1], v[10:11]
	v_pk_mul_f32 v[28:29], s[54:55], v[8:9]
	v_pk_mul_f32 v[26:27], s[0:1], v[2:3]
	v_pk_mul_f32 v[24:25], s[54:55], v[0:1]
.LBB0_807:
	v_lshlrev_b64 v[0:1], 10, v[72:73]
	v_lshl_add_u64 v[4:5], v[94:95], 0, v[0:1]
	v_cvt_pk_bf16_f32 v0, v36, v37
	v_cvt_pk_bf16_f32 v1, v38, v39
	v_cvt_pk_bf16_f32 v2, v32, v33
	v_cvt_pk_bf16_f32 v3, v34, v35
	s_andn2_b64 vcc, exec, s[4:5]
	s_mov_b64 s[0:1], -1
	global_store_dwordx4 v[4:5], v[0:3], off sc1
	s_nop 1
	v_cvt_pk_bf16_f32 v0, v28, v29
	v_cvt_pk_bf16_f32 v1, v30, v31
	v_cvt_pk_bf16_f32 v2, v24, v25
	v_cvt_pk_bf16_f32 v3, v26, v27
	global_store_dwordx4 v[4:5], v[0:3], off offset:64 sc1
	s_cbranch_vccnz .LBB0_747
	s_andn2_b64 vcc, exec, s[16:17]
	s_cbranch_vccnz .LBB0_746
	s_barrier
	s_branch .LBB0_746
